# v19: conflict-free LDS layout for the per-pass wave-pair partial-output exchange (64-B lane stride -> 16-B lane stride)
# speedup vs baseline: 1.0178x; 1.0041x over previous
; #define XS_WRITE(OV, BASE) do { float* xs_ = (float*)(lds + (BASE)) + ((g * 4) * 64 + lane) * 16; \
;     _Pragma("unroll") for (int d0 = 0; d0 < 4; ++d0) { float* xp = xs_ + d0 * 64 * 16; \
;       _Pragma("unroll") for (int q4 = 0; q4 < 4; ++q4) *(f32x4v*)(xp + 4 * q4) = (f32x4v){OV[d0][4 * q4], OV[d0][4 * q4 + 1], OV[d0][4 * q4 + 2], OV[d0][4 * q4 + 3]}; } } while (0)
; #define XS_WRITE(OV, BASE) do { float* xs_ = (float*)(lds + (BASE)) + ((g * 4) * 64 + lane) * 16; \
;     _Pragma("unroll") for (int d0 = 0; d0 < 4; ++d0) { float* xp = xs_ + d0 * 64 * 16; \
;       _Pragma("unroll") for (int q4 = 0; q4 < 4; ++q4) *(f32x4v*)(xp + 4 * q4) = (f32x4v){OV[d0][4 * q4], OV[d0][4 * q4 + 1], OV[d0][4 * q4 + 2], OV[d0][4 * q4 + 3]}; } } while (0)
; template <int MODE> ...
;     ...
;   L_lds[(wid * 2 + hi) * 32 + r32] = lsum;
;     ...
;   f32x16* olo = o; f32x16* ohi = o + 4;
;   if (kh) { XS_WRITE(olo, 0); } else { XS_WRITE(ohi, 65536); }
;   __syncthreads();
;   if (kh) { XS_ADD(ohi, 65536);
; #pragma unroll
;     for (int d0 = 0; d0 < 4; ++d0) o[d0] = o[4 + d0]; }
;   else { XS_ADD(olo, 0); }
.Lattn_join_m0:
	v_mov_b32_e32 v172, v215
	s_setprio 0
	v_lshl_add_u32 v128, v197, 2, 0
	v_add_u32_e32 v128, 0x20000, v128
	v_mov_b32_e32 v129, s65
	v_cmp_eq_u32_e32 vcc, 0, v211
	ds_write_b32 v128, v172
	v_lshlrev_b32_e32 v128, 14, v213
	v_cndmask_b32_e32 v131, 0, v129, vcc
	v_lshlrev_b32_e32 v130, 0, v212
	v_cndmask_b32_e32 v147, v115, v51, vcc
	v_cndmask_b32_e32 v146, v114, v50, vcc
	v_cndmask_b32_e32 v145, v113, v49, vcc
	v_cndmask_b32_e32 v144, v112, v48, vcc
	v_add3_u32 v131, v131, v128, v130
	v_cndmask_b32_e32 v135, v127, v63, vcc
	v_cndmask_b32_e32 v134, v126, v62, vcc
	v_cndmask_b32_e32 v133, v125, v61, vcc
	v_cndmask_b32_e32 v132, v124, v60, vcc
	v_cndmask_b32_e32 v139, v123, v59, vcc
	v_cndmask_b32_e32 v138, v122, v58, vcc
	v_cndmask_b32_e32 v137, v121, v57, vcc
	v_cndmask_b32_e32 v136, v120, v56, vcc
	v_cndmask_b32_e32 v143, v119, v55, vcc
	v_cndmask_b32_e32 v142, v118, v54, vcc
	v_cndmask_b32_e32 v141, v117, v53, vcc
	v_cndmask_b32_e32 v140, v116, v52, vcc
	v_cndmask_b32_e32 v151, v111, v47, vcc
	v_cndmask_b32_e32 v150, v110, v46, vcc
	v_cndmask_b32_e32 v149, v109, v45, vcc
	v_cndmask_b32_e32 v148, v108, v44, vcc
	v_cndmask_b32_e32 v155, v107, v43, vcc
	v_cndmask_b32_e32 v154, v106, v42, vcc
	v_cndmask_b32_e32 v153, v105, v41, vcc
	v_cndmask_b32_e32 v152, v104, v40, vcc
	v_cndmask_b32_e32 v159, v103, v39, vcc
	v_cndmask_b32_e32 v158, v102, v38, vcc
	v_cndmask_b32_e32 v157, v101, v37, vcc
	v_cndmask_b32_e32 v156, v100, v36, vcc
	v_cndmask_b32_e32 v163, v99, v35, vcc
	v_cndmask_b32_e32 v162, v98, v34, vcc
	v_cndmask_b32_e32 v161, v97, v33, vcc
	v_cndmask_b32_e32 v160, v96, v32, vcc
	v_cndmask_b32_e32 v167, v95, v31, vcc
	v_cndmask_b32_e32 v166, v94, v30, vcc
	v_cndmask_b32_e32 v165, v93, v29, vcc
	v_cndmask_b32_e32 v164, v92, v28, vcc
	v_cndmask_b32_e32 v171, v91, v27, vcc
	v_cndmask_b32_e32 v170, v90, v26, vcc
	v_cndmask_b32_e32 v169, v89, v25, vcc
	v_cndmask_b32_e32 v168, v88, v24, vcc
	v_cndmask_b32_e32 v175, v87, v23, vcc
	v_cndmask_b32_e32 v174, v86, v22, vcc
	v_cndmask_b32_e32 v173, v85, v21, vcc
	v_cndmask_b32_e32 v172, v84, v20, vcc
	v_cndmask_b32_e32 v179, v83, v19, vcc
	v_cndmask_b32_e32 v178, v82, v18, vcc
	v_cndmask_b32_e32 v177, v81, v17, vcc
	v_cndmask_b32_e32 v176, v80, v16, vcc
	v_cndmask_b32_e32 v183, v79, v15, vcc
	v_cndmask_b32_e32 v182, v78, v14, vcc
	v_cndmask_b32_e32 v181, v77, v13, vcc
	v_cndmask_b32_e32 v180, v76, v12, vcc
	v_cndmask_b32_e32 v187, v75, v11, vcc
	v_cndmask_b32_e32 v186, v74, v10, vcc
	v_cndmask_b32_e32 v185, v73, v9, vcc
	v_cndmask_b32_e32 v184, v72, v8, vcc
	v_cndmask_b32_e32 v191, v71, v7, vcc
	v_cndmask_b32_e32 v190, v70, v6, vcc
	v_cndmask_b32_e32 v189, v69, v5, vcc
	v_cndmask_b32_e32 v188, v68, v4, vcc
	v_cndmask_b32_e32 v201, v67, v3, vcc
	v_cndmask_b32_e32 v200, v66, v2, vcc
	v_cndmask_b32_e32 v199, v65, v1, vcc
	v_cndmask_b32_e32 v198, v64, v0, vcc
	ds_write_b128 v131, v[144:147]
	ds_write_b128 v131, v[140:143] offset:1024
	ds_write_b128 v131, v[136:139] offset:2048
	ds_write_b128 v131, v[132:135] offset:3072
	ds_write_b128 v131, v[160:163] offset:4096
	ds_write_b128 v131, v[156:159] offset:5120
	ds_write_b128 v131, v[152:155] offset:6144
	ds_write_b128 v131, v[148:151] offset:7168
	ds_write_b128 v131, v[176:179] offset:8192
	ds_write_b128 v131, v[172:175] offset:9216
	ds_write_b128 v131, v[168:171] offset:10240
	ds_write_b128 v131, v[164:167] offset:11264
	ds_write_b128 v131, v[198:201] offset:12288
	ds_write_b128 v131, v[188:191] offset:13312
	ds_write_b128 v131, v[184:187] offset:14336
	ds_write_b128 v131, v[180:183] offset:15360
	s_waitcnt vmcnt(0) lgkmcnt(0)
	s_barrier
	s_and_saveexec_b64 s[24:25], vcc
	s_cbranch_execz .LBB0_1022
	v_mov_b64_e32 v[48:49], v[112:113]
	v_mov_b64_e32 v[32:33], v[96:97]
	v_mov_b64_e32 v[16:17], v[80:81]
	v_mov_b64_e32 v[0:1], v[64:65]
	v_mov_b32_e32 v129, 0
	v_mov_b64_e32 v[50:51], v[114:115]
	v_mov_b64_e32 v[52:53], v[116:117]
	v_mov_b64_e32 v[54:55], v[118:119]
	v_mov_b64_e32 v[56:57], v[120:121]
	v_mov_b64_e32 v[58:59], v[122:123]
	v_mov_b64_e32 v[60:61], v[124:125]
	v_mov_b64_e32 v[62:63], v[126:127]
	v_mov_b64_e32 v[34:35], v[98:99]
	v_mov_b64_e32 v[36:37], v[100:101]
	v_mov_b64_e32 v[38:39], v[102:103]
	v_mov_b64_e32 v[40:41], v[104:105]
	v_mov_b64_e32 v[42:43], v[106:107]
	v_mov_b64_e32 v[44:45], v[108:109]
	v_mov_b64_e32 v[46:47], v[110:111]
	v_mov_b64_e32 v[18:19], v[82:83]
	v_mov_b64_e32 v[20:21], v[84:85]
	v_mov_b64_e32 v[22:23], v[86:87]
	v_mov_b64_e32 v[24:25], v[88:89]
	v_mov_b64_e32 v[26:27], v[90:91]
	v_mov_b64_e32 v[28:29], v[92:93]
	v_mov_b64_e32 v[30:31], v[94:95]
	v_mov_b64_e32 v[2:3], v[66:67]
	v_mov_b64_e32 v[4:5], v[68:69]
	v_mov_b64_e32 v[6:7], v[70:71]
	v_mov_b64_e32 v[8:9], v[72:73]
	v_mov_b64_e32 v[10:11], v[74:75]
	v_mov_b64_e32 v[12:13], v[76:77]
	v_mov_b64_e32 v[14:15], v[78:79]
; __device__ __forceinline__ int crow(int r, int hi) { return (r & 3) + 8 * (r >> 2) + 4 * hi; }
; #define XS_WRITE(OV, BASE) do { float* xs_ = (float*)(lds + (BASE)) + ((g * 4) * 64 + lane) * 16; \
;     _Pragma("unroll") for (int d0 = 0; d0 < 4; ++d0) { float* xp = xs_ + d0 * 64 * 16; \
;       _Pragma("unroll") for (int q4 = 0; q4 < 4; ++q4) *(f32x4v*)(xp + 4 * q4) = (f32x4v){OV[d0][4 * q4], OV[d0][4 * q4 + 1], OV[d0][4 * q4 + 2], OV[d0][4 * q4 + 3]}; } } while (0)
; #define XS_WRITE(OV, BASE) do { float* xs_ = (float*)(lds + (BASE)) + ((g * 4) * 64 + lane) * 16; \
;     _Pragma("unroll") for (int d0 = 0; d0 < 4; ++d0) { float* xp = xs_ + d0 * 64 * 16; \
;       _Pragma("unroll") for (int q4 = 0; q4 < 4; ++q4) *(f32x4v*)(xp + 4 * q4) = (f32x4v){OV[d0][4 * q4], OV[d0][4 * q4 + 1], OV[d0][4 * q4 + 2], OV[d0][4 * q4 + 3]}; } } while (0)
; template <int MODE> ...
;     ...
;   f32x16* olo = o; f32x16* ohi = o + 4;
;   if (kh) { XS_WRITE(olo, 0); } else { XS_WRITE(ohi, 65536); }
;   __syncthreads();
;   if (kh) { XS_ADD(ohi, 65536);
; #pragma unroll
;     for (int d0 = 0; d0 < 4; ++d0) o[d0] = o[4 + d0]; }
;   else { XS_ADD(olo, 0); }
;     ...
;   float rli[16];
; #pragma unroll
;   for (int r = 0; r < 16; ++r) { const int row = crow(r, hi); const float* lp = L_lds + (g * 4) * 32 + row; rli[r] = __builtin_amdgcn_rcpf((lp[0] + lp[32]) + (lp[64] + lp[96])); }
.LBB0_1022:
	s_or_b64 exec, exec, s[24:25]
	v_add3_u32 v80, v129, v128, v130
	ds_read_b128 v[64:67], v80
	ds_read_b128 v[68:71], v80 offset:1024
	ds_read_b128 v[72:75], v80 offset:2048
	ds_read_b128 v[76:79], v80 offset:3072
	s_ashr_i32 s24, s40, 3
	s_ashr_i32 s25, s24, 31
	s_waitcnt lgkmcnt(2)
	v_add_f32_e32 v68, v52, v68
	v_add_f32_e32 v64, v48, v64
	v_add_f32_e32 v65, v49, v65
	v_add_f32_e32 v66, v50, v66
	v_add_f32_e32 v67, v51, v67
	ds_read_b128 v[48:51], v80 offset:4096
	v_add_f32_e32 v69, v53, v69
	v_add_f32_e32 v70, v54, v70
	v_add_f32_e32 v71, v55, v71
	ds_read_b128 v[52:55], v80 offset:5120
	s_waitcnt lgkmcnt(1)
	v_add_f32_e32 v48, v32, v48
	v_add_f32_e32 v49, v33, v49
	v_add_f32_e32 v50, v34, v50
	v_add_f32_e32 v51, v35, v51
	ds_read_b128 v[32:35], v80 offset:6144
	s_waitcnt lgkmcnt(1)
	v_add_f32_e32 v52, v36, v52
	v_add_f32_e32 v53, v37, v53
	v_add_f32_e32 v54, v38, v54
	v_add_f32_e32 v55, v39, v55
	ds_read_b128 v[36:39], v80 offset:7168
	s_waitcnt lgkmcnt(1)
	v_add_f32_e32 v40, v40, v32
	v_add_f32_e32 v41, v41, v33
	v_add_f32_e32 v42, v42, v34
	v_add_f32_e32 v43, v43, v35
	ds_read_b128 v[32:35], v80 offset:8192
	s_waitcnt lgkmcnt(1)
	v_add_f32_e32 v44, v44, v36
	v_add_f32_e32 v45, v45, v37
	v_add_f32_e32 v46, v46, v38
	v_add_f32_e32 v47, v47, v39
	ds_read_b128 v[36:39], v80 offset:9216
	s_waitcnt lgkmcnt(1)
	v_add_f32_e32 v32, v16, v32
	v_add_f32_e32 v33, v17, v33
	v_add_f32_e32 v34, v18, v34
	v_add_f32_e32 v35, v19, v35
	ds_read_b128 v[16:19], v80 offset:10240
	s_waitcnt lgkmcnt(1)
	v_add_f32_e32 v36, v20, v36
	v_add_f32_e32 v37, v21, v37
	v_add_f32_e32 v38, v22, v38
	v_add_f32_e32 v39, v23, v39
	ds_read_b128 v[20:23], v80 offset:11264
	v_add_f32_e32 v56, v56, v72
	v_add_f32_e32 v57, v57, v73
	v_add_f32_e32 v58, v58, v74
	v_add_f32_e32 v59, v59, v75
	s_waitcnt lgkmcnt(1)
	v_add_f32_e32 v72, v24, v16
	v_add_f32_e32 v73, v25, v17
	v_add_f32_e32 v74, v26, v18
	v_add_f32_e32 v75, v27, v19
	ds_read_b128 v[16:19], v80 offset:12288
	v_add_f32_e32 v60, v60, v76
	v_add_f32_e32 v61, v61, v77
	v_add_f32_e32 v62, v62, v78
	v_add_f32_e32 v63, v63, v79
	s_waitcnt lgkmcnt(1)
	v_add_f32_e32 v76, v28, v20
	v_add_f32_e32 v77, v29, v21
	v_add_f32_e32 v78, v30, v22
	v_add_f32_e32 v79, v31, v23
	ds_read_b128 v[20:23], v80 offset:13312
	s_lshl_b32 s2, s40, 8
	s_and_b32 s94, s2, 0x700
	s_lshl_b64 s[2:3], s[24:25], 27
	s_lshl_b64 s[28:29], s[28:29], 20
	s_waitcnt lgkmcnt(1)
	v_add_f32_e32 v81, v0, v16
	v_add_f32_e32 v82, v1, v17
	v_add_f32_e32 v83, v2, v18
	v_add_f32_e32 v84, v3, v19
	ds_read_b128 v[0:3], v80 offset:14336
	s_add_u32 s2, s38, s2
	s_addc_u32 s3, s39, s3
	s_add_u32 s2, s2, s28
	s_waitcnt lgkmcnt(1)
	v_add_f32_e32 v85, v4, v20
	v_add_f32_e32 v86, v5, v21
	v_add_f32_e32 v87, v6, v22
	v_add_f32_e32 v88, v7, v23
	ds_read_b128 v[4:7], v80 offset:15360
	s_addc_u32 s3, s3, s29
	s_lshl_b32 s25, s94, 2
	s_add_u32 s28, s2, s25
	s_waitcnt lgkmcnt(1)
	v_add_f32_e32 v80, v8, v0
	v_and_b32_e32 v0, 0x3fffff80, v197
	s_addc_u32 s29, s3, 0
	v_lshlrev_b32_e32 v0, 2, v0
	s_add_i32 s25, 0, 0x20000
	v_add3_u32 v96, s25, v0, v194
	v_add_f32_e32 v89, v9, v1
	v_add_f32_e32 v90, v10, v2
	v_add_f32_e32 v91, v11, v3
	s_waitcnt lgkmcnt(0)
	v_add_f32_e32 v92, v12, v4
	v_add_f32_e32 v93, v13, v5
	v_add_f32_e32 v94, v14, v6
	v_add_f32_e32 v95, v15, v7
	ds_read_b128 v[0:3], v96 offset:128
	ds_read_b128 v[4:7], v96
	ds_read_b128 v[8:11], v96 offset:32
	ds_read_b128 v[12:15], v96 offset:256
	ds_read_b128 v[16:19], v96 offset:384
	ds_read_b128 v[20:23], v96 offset:160
	s_waitcnt lgkmcnt(4)
	v_add_f32_e32 v0, v4, v0
	ds_read_b128 v[24:27], v96 offset:288
	ds_read_b128 v[28:31], v96 offset:416
	v_ashrrev_i32_e32 v197, 31, v196
	s_waitcnt lgkmcnt(3)
	v_add_f32_e32 v4, v12, v16
	v_add_f32_e32 v0, v0, v4
	v_rcp_f32_e32 v97, v0
	v_add_f32_e32 v0, v5, v1
	v_add_f32_e32 v1, v13, v17
	v_add_f32_e32 v0, v0, v1
	v_rcp_f32_e32 v98, v0
	v_add_f32_e32 v0, v6, v2
	v_add_f32_e32 v1, v14, v18
	v_add_f32_e32 v0, v0, v1
	v_rcp_f32_e32 v99, v0
	v_add_f32_e32 v0, v7, v3
	v_add_f32_e32 v1, v15, v19
	v_add_f32_e32 v0, v0, v1
	v_rcp_f32_e32 v100, v0
	s_waitcnt lgkmcnt(2)
	v_add_f32_e32 v0, v8, v20
	s_waitcnt lgkmcnt(0)
	v_add_f32_e32 v1, v24, v28
	v_add_f32_e32 v0, v0, v1
	v_rcp_f32_e32 v101, v0
	v_add_f32_e32 v0, v9, v21
	v_add_f32_e32 v1, v25, v29
	v_add_f32_e32 v0, v0, v1
	v_rcp_f32_e32 v102, v0
	v_add_f32_e32 v0, v10, v22
	v_add_f32_e32 v1, v26, v30
	v_add_f32_e32 v0, v0, v1
	v_rcp_f32_e32 v103, v0
	v_add_f32_e32 v0, v11, v23
	v_add_f32_e32 v1, v27, v31
	v_add_f32_e32 v0, v0, v1
	v_rcp_f32_e32 v104, v0
	ds_read_b128 v[0:3], v96 offset:64
	ds_read_b128 v[4:7], v96 offset:192
	ds_read_b128 v[8:11], v96 offset:320
	ds_read_b128 v[12:15], v96 offset:448
	ds_read_b128 v[16:19], v96 offset:96
	ds_read_b128 v[20:23], v96 offset:224
	s_waitcnt lgkmcnt(4)
	v_add_f32_e32 v0, v0, v4
	ds_read_b128 v[24:27], v96 offset:352
	ds_read_b128 v[28:31], v96 offset:480
	s_waitcnt lgkmcnt(4)
	v_add_f32_e32 v4, v8, v12
	v_add_f32_e32 v0, v0, v4
	v_rcp_f32_e32 v4, v0
	v_add_f32_e32 v0, v1, v5
	v_add_f32_e32 v1, v9, v13
	v_add_f32_e32 v0, v0, v1
	v_rcp_f32_e32 v5, v0
	v_add_f32_e32 v0, v2, v6
	v_add_f32_e32 v1, v10, v14
	v_add_f32_e32 v0, v0, v1
	v_rcp_f32_e32 v6, v0
	v_add_f32_e32 v0, v3, v7
	v_add_f32_e32 v1, v11, v15
	v_add_f32_e32 v0, v0, v1
	v_rcp_f32_e32 v7, v0
	s_waitcnt lgkmcnt(2)
	v_add_f32_e32 v0, v16, v20
	s_waitcnt lgkmcnt(0)
; __device__ __forceinline__ int crow(int r, int hi) { return (r & 3) + 8 * (r >> 2) + 4 * hi; }
; template <int MODE> ...
;     ...
;   for (int r = 0; r < 16; ++r) { const int row = crow(r, hi); const float* lp = L_lds + (g * 4) * 32 + row; rli[r] = __builtin_amdgcn_rcpf((lp[0] + lp[32]) + (lp[64] + lp[96])); }
;   float* Ow = Ob + (long)(g * 32) * LDO + kh * 128;
;   if (MODE == 0) {
; #pragma unroll
;     for (int r = 0; r < 16; ++r) { const int orow = crow(r, hi);
; #pragma unroll
;       for (int d0 = 0; d0 < 4; ++d0) Ow[(long)orow * LDO + d0 * 32 + r32] = o[d0][r] * rli[r]; }
;     asm volatile("s_waitcnt vmcnt(0)" ::: "memory"); __syncthreads();
	v_add_f32_e32 v1, v24, v28
	v_add_f32_e32 v0, v0, v1
	v_rcp_f32_e32 v8, v0
	v_add_f32_e32 v0, v17, v21
	v_add_f32_e32 v1, v25, v29
	v_add_f32_e32 v0, v0, v1
	v_rcp_f32_e32 v9, v0
	v_add_f32_e32 v0, v18, v22
	v_add_f32_e32 v1, v26, v30
	v_add_f32_e32 v0, v0, v1
	v_rcp_f32_e32 v10, v0
	v_add_f32_e32 v0, v19, v23
	v_add_f32_e32 v1, v27, v31
	v_add_f32_e32 v0, v0, v1
	v_rcp_f32_e32 v11, v0
	v_lshlrev_b64 v[0:1], 13, v[196:197]
	v_lshl_add_u64 v[0:1], s[28:29], 0, v[0:1]
	v_lshlrev_b32_e32 v194, 9, v211
	v_lshl_add_u64 v[0:1], v[0:1], 0, v[194:195]
	v_lshlrev_b32_e32 v194, 2, v206
	v_lshlrev_b32_e32 v2, 15, v207
	v_lshl_add_u64 v[0:1], v[0:1], 0, v[194:195]
	v_mov_b32_e32 v3, v195
	v_lshl_add_u64 v[0:1], v[0:1], 0, v[2:3]
	v_mul_f32_e32 v2, v64, v97
	global_store_dword v[0:1], v2, off
	v_mul_f32_e32 v2, v48, v97
	global_store_dword v[0:1], v2, off offset:128
	v_mul_f32_e32 v2, v32, v97
	global_store_dword v[0:1], v2, off offset:256
	v_mul_f32_e32 v2, v81, v97
	global_store_dword v[0:1], v2, off offset:384
	v_add_co_u32_e32 v2, vcc, s57, v0
	v_mul_f32_e32 v12, v65, v98
	s_nop 0
	v_addc_co_u32_e32 v3, vcc, 0, v1, vcc
	global_store_dword v[2:3], v12, off
	v_mul_f32_e32 v12, v49, v98
	global_store_dword v[2:3], v12, off offset:128
	v_mul_f32_e32 v12, v33, v98
	global_store_dword v[2:3], v12, off offset:256
	v_mul_f32_e32 v12, v82, v98
	global_store_dword v[2:3], v12, off offset:384
	v_add_co_u32_e32 v2, vcc, s62, v0
	v_mul_f32_e32 v12, v66, v99
	s_nop 0
	v_addc_co_u32_e32 v3, vcc, 0, v1, vcc
	global_store_dword v[2:3], v12, off
	v_mul_f32_e32 v12, v50, v99
	global_store_dword v[2:3], v12, off offset:128
	v_mul_f32_e32 v12, v34, v99
	global_store_dword v[2:3], v12, off offset:256
	v_mul_f32_e32 v12, v83, v99
	global_store_dword v[2:3], v12, off offset:384
	v_add_co_u32_e32 v2, vcc, s66, v0
	v_mul_f32_e32 v12, v67, v100
	s_nop 0
	v_addc_co_u32_e32 v3, vcc, 0, v1, vcc
	global_store_dword v[2:3], v12, off
	v_mul_f32_e32 v12, v51, v100
	global_store_dword v[2:3], v12, off offset:128
	v_mul_f32_e32 v12, v35, v100
	global_store_dword v[2:3], v12, off offset:256
	v_mul_f32_e32 v12, v84, v100
	global_store_dword v[2:3], v12, off offset:384
	v_add_co_u32_e32 v2, vcc, s64, v0
	v_mul_f32_e32 v12, v68, v101
	s_nop 0
	v_addc_co_u32_e32 v3, vcc, 0, v1, vcc
	global_store_dword v[2:3], v12, off
	v_mul_f32_e32 v12, v52, v101
	global_store_dword v[2:3], v12, off offset:128
	v_mul_f32_e32 v12, v36, v101
	global_store_dword v[2:3], v12, off offset:256
	v_mul_f32_e32 v12, v85, v101
	global_store_dword v[2:3], v12, off offset:384
	v_add_co_u32_e32 v2, vcc, s67, v0
	v_mul_f32_e32 v12, v69, v102
	s_nop 0
	v_addc_co_u32_e32 v3, vcc, 0, v1, vcc
	global_store_dword v[2:3], v12, off
	v_mul_f32_e32 v12, v53, v102
	global_store_dword v[2:3], v12, off offset:128
	v_mul_f32_e32 v12, v37, v102
	global_store_dword v[2:3], v12, off offset:256
	v_mul_f32_e32 v12, v86, v102
	global_store_dword v[2:3], v12, off offset:384
	v_add_co_u32_e32 v2, vcc, s68, v0
	v_mul_f32_e32 v12, v70, v103
	s_nop 0
	v_addc_co_u32_e32 v3, vcc, 0, v1, vcc
	global_store_dword v[2:3], v12, off
	v_mul_f32_e32 v12, v54, v103
	global_store_dword v[2:3], v12, off offset:128
	v_mul_f32_e32 v12, v38, v103
	global_store_dword v[2:3], v12, off offset:256
	v_mul_f32_e32 v12, v87, v103
	global_store_dword v[2:3], v12, off offset:384
	v_add_co_u32_e32 v2, vcc, s69, v0
	v_mul_f32_e32 v12, v71, v104
	s_nop 0
	v_addc_co_u32_e32 v3, vcc, 0, v1, vcc
	global_store_dword v[2:3], v12, off
	v_mul_f32_e32 v12, v55, v104
	global_store_dword v[2:3], v12, off offset:128
	v_mul_f32_e32 v12, v39, v104
	global_store_dword v[2:3], v12, off offset:256
	v_mul_f32_e32 v12, v88, v104
	global_store_dword v[2:3], v12, off offset:384
	v_add_co_u32_e32 v2, vcc, s63, v0
	v_mul_f32_e32 v12, v56, v4
	s_nop 0
	v_addc_co_u32_e32 v3, vcc, 0, v1, vcc
	global_store_dword v[2:3], v12, off
	v_mul_f32_e32 v12, v40, v4
	global_store_dword v[2:3], v12, off offset:128
	v_mul_f32_e32 v12, v72, v4
	v_mul_f32_e32 v4, v80, v4
	global_store_dword v[2:3], v12, off offset:256
	global_store_dword v[2:3], v4, off offset:384
	v_add_co_u32_e32 v2, vcc, s70, v0
	v_mul_f32_e32 v4, v57, v5
	s_nop 0
	v_addc_co_u32_e32 v3, vcc, 0, v1, vcc
	global_store_dword v[2:3], v4, off
	v_mul_f32_e32 v4, v41, v5
	global_store_dword v[2:3], v4, off offset:128
	v_mul_f32_e32 v4, v73, v5
	global_store_dword v[2:3], v4, off offset:256
	v_mul_f32_e32 v4, v89, v5
	global_store_dword v[2:3], v4, off offset:384
	v_add_co_u32_e32 v2, vcc, s71, v0
	v_mul_f32_e32 v4, v58, v6
	s_nop 0
	v_addc_co_u32_e32 v3, vcc, 0, v1, vcc
	global_store_dword v[2:3], v4, off
	v_mul_f32_e32 v4, v42, v6
	global_store_dword v[2:3], v4, off offset:128
	v_mul_f32_e32 v4, v74, v6
	global_store_dword v[2:3], v4, off offset:256
	v_mul_f32_e32 v4, v90, v6
	global_store_dword v[2:3], v4, off offset:384
	v_add_co_u32_e32 v2, vcc, s72, v0
	v_mul_f32_e32 v4, v59, v7
	s_nop 0
	v_addc_co_u32_e32 v3, vcc, 0, v1, vcc
	global_store_dword v[2:3], v4, off
	v_mul_f32_e32 v4, v43, v7
	global_store_dword v[2:3], v4, off offset:128
	v_mul_f32_e32 v4, v75, v7
	global_store_dword v[2:3], v4, off offset:256
	v_mul_f32_e32 v4, v91, v7
	global_store_dword v[2:3], v4, off offset:384
	v_add_co_u32_e32 v2, vcc, s73, v0
	v_mul_f32_e32 v4, v60, v8
	s_nop 0
	v_addc_co_u32_e32 v3, vcc, 0, v1, vcc
	global_store_dword v[2:3], v4, off
	v_mul_f32_e32 v4, v44, v8
	global_store_dword v[2:3], v4, off offset:128
	v_mul_f32_e32 v4, v76, v8
	global_store_dword v[2:3], v4, off offset:256
	v_mul_f32_e32 v4, v92, v8
	global_store_dword v[2:3], v4, off offset:384
	v_add_co_u32_e32 v2, vcc, s74, v0
	v_mul_f32_e32 v4, v61, v9
	s_nop 0
	v_addc_co_u32_e32 v3, vcc, 0, v1, vcc
	global_store_dword v[2:3], v4, off
	v_mul_f32_e32 v4, v45, v9
	global_store_dword v[2:3], v4, off offset:128
	v_mul_f32_e32 v4, v77, v9
	global_store_dword v[2:3], v4, off offset:256
	v_mul_f32_e32 v4, v93, v9
	global_store_dword v[2:3], v4, off offset:384
	v_add_co_u32_e32 v2, vcc, s75, v0
	v_mul_f32_e32 v4, v62, v10
	s_nop 0
	v_addc_co_u32_e32 v3, vcc, 0, v1, vcc
	global_store_dword v[2:3], v4, off
	v_mul_f32_e32 v4, v46, v10
	global_store_dword v[2:3], v4, off offset:128
	v_mul_f32_e32 v4, v78, v10
	global_store_dword v[2:3], v4, off offset:256
	v_mul_f32_e32 v4, v94, v10
	v_add_co_u32_e32 v0, vcc, s76, v0
	global_store_dword v[2:3], v4, off offset:384
	v_mul_f32_e32 v2, v63, v11
	v_addc_co_u32_e32 v1, vcc, 0, v1, vcc
	global_store_dword v[0:1], v2, off
	v_mul_f32_e32 v2, v47, v11
	global_store_dword v[0:1], v2, off offset:128
	v_mul_f32_e32 v2, v79, v11
	global_store_dword v[0:1], v2, off offset:256
	v_mul_f32_e32 v2, v95, v11
	global_store_dword v[0:1], v2, off offset:384
	v_mov_b32_e32 v194, v224
	s_waitcnt vmcnt(0)
	s_waitcnt vmcnt(63) expcnt(7) lgkmcnt(15)
	s_barrier
; __device__ __forceinline__ int v_rd_base(int lane) { return ((lane & 3) << 3) | (((lane >> 2) & 3) << 6) | (((lane >> 4) & 1) << 5) | (((lane >> 5) & 1) << 8); }
; #define RAWBAR() do { asm volatile("s_waitcnt lgkmcnt(0)" ::: "memory"); __builtin_amdgcn_s_barrier(); asm volatile("" ::: "memory"); } while (0)
; #define RAWBAR() do { asm volatile("s_waitcnt lgkmcnt(0)" ::: "memory"); __builtin_amdgcn_s_barrier(); asm volatile("" ::: "memory"); } while (0)
; #define RAWBAR() do { asm volatile("s_waitcnt lgkmcnt(0)" ::: "memory"); __builtin_amdgcn_s_barrier(); asm volatile("" ::: "memory"); } while (0)
; #define RAWBAR() do { asm volatile("s_waitcnt lgkmcnt(0)" ::: "memory"); __builtin_amdgcn_s_barrier(); asm volatile("" ::: "memory"); } while (0)
; #define RAWBAR() do { asm volatile("s_waitcnt lgkmcnt(0)" ::: "memory"); __builtin_amdgcn_s_barrier(); asm volatile("" ::: "memory"); } while (0)
; #define RAWBAR() do { asm volatile("s_waitcnt lgkmcnt(0)" ::: "memory"); __builtin_amdgcn_s_barrier(); asm volatile("" ::: "memory"); } while (0)
; template <int MODE> ...
;     ...
;   const bf16* Qw = Qb + (long)(g * 32 + r32) * 128 + hi * 8;
; #pragma unroll
;   for (int d0 = 0; d0 < 8; ++d0) qr[d0] = St::ld8(Qw + d0 * 16);
;   const int vb0 = (int)(uintptr_t)V_lds + v_rd_base(lane) + 2 * kh * 4096;
;   const int krow = 32 * kh + r32;
;   typedef __attribute__((address_space(3))) unsigned lds_u32;
;   const int wu = __builtin_amdgcn_readfirstlane(wid);
;   long gk[2], gv[2];
; #pragma unroll
;   for (int c = 0; c < 2; ++c) { const int q = wu + 8 * c;
;     const int r = 4 * q + (lane >> 4), pch = lane & 15; gk[c] = (long)r * 128 + ((pch ^ (r & 7)) * 8);
;     const int st = 2 * q + (lane >> 5), kk = (st >> 2) * 8 + ((lane >> 2) & 7), k = (kk & ~0xC) | ((kk & 4) << 1) | ((kk & 8) >> 1), cc = (st & 3) * 32 + (lane & 3) * 8;
;     gv[c] = (long)k * 256 + cc; }
;     ...
;   const int NT = seq / KVBLK;
;   STAGE(0, 0); asm volatile("s_waitcnt vmcnt(0)" ::: "memory"); RAWBAR();
	v_mov_b32_e32 v199, v195
	v_ashrrev_i32_e32 v217, 7, v194
	v_and_b32_e32 v214, 31, v194
	v_lshlrev_b32_e32 v196, 5, v217
	v_or_b32_e32 v0, v196, v214
	v_ashrrev_i32_e32 v1, 31, v0
	v_bfe_u32 v213, v194, 5, 1
	v_lshlrev_b64 v[0:1], 8, v[0:1]
	v_lshl_add_u64 v[0:1], s[34:35], 0, v[0:1]
	v_lshlrev_b32_e32 v198, 4, v213
	v_lshl_add_u64 v[0:1], v[0:1], 0, v[198:199]
	v_lshl_add_u64 v[2:3], v[0:1], 0, s[20:21]
	v_add_co_u32_e32 v0, vcc, s77, v0
	v_ashrrev_i32_e32 v215, 6, v194
	s_add_u32 s36, s36, 0x410000
	v_addc_co_u32_e32 v1, vcc, 0, v1, vcc
	v_readfirstlane_b32 s2, v215
	s_addc_u32 s37, s37, 0
	global_load_dwordx4 v[184:187], v[2:3], off offset:32
	global_load_dwordx4 v[180:183], v[2:3], off offset:64
	global_load_dwordx4 v[176:179], v[2:3], off offset:96
	global_load_dwordx4 v[172:175], v[2:3], off offset:128
	global_load_dwordx4 v[168:171], v[2:3], off offset:160
	global_load_dwordx4 v[164:167], v[2:3], off offset:192
	global_load_dwordx4 v[188:191], v[0:1], off
	global_load_dwordx4 v[160:163], v[2:3], off offset:224
	v_bfe_u32 v199, v194, 4, 2
	v_bfe_u32 v0, v194, 2, 2
	v_lshrrev_b32_e32 v1, 1, v194
	s_lshl_b32 s3, s2, 2
	s_lshl_b32 s34, s2, 1
	v_and_or_b32 v6, v1, 8, v0
	v_or_b32_e32 v0, s3, v199
	s_and_b32 s3, s3, -16
	s_and_b32 s35, s34, 4
	s_or_b32 s3, s3, s35
	v_or_b32_e32 v2, s3, v6
	s_add_i32 s3, s2, 8
	v_and_b32_e32 v4, 63, v194
	v_and_or_b32 v14, s34, 2, v213
	s_lshl_b32 s34, s3, 2
	s_lshl_b32 s35, s3, 1
	v_lshlrev_b32_e32 v8, 3, v4
	v_lshlrev_b32_e32 v197, 4, v4
	v_or_b32_e32 v4, s34, v199
	s_and_b32 s34, s34, -16
	s_and_b32 s41, s35, 4
	v_lshlrev_b32_e32 v9, 1, v194
	v_and_b32_e32 v211, 15, v194
	v_ashrrev_i32_e32 v1, 31, v0
	s_or_b32 s34, s34, s41
	v_and_b32_e32 v12, 0x100, v8
	v_bitop3_b32 v10, v0, v211, 7 bitop3:0x6c
	v_ashrrev_i32_e32 v5, 31, v4
	v_bitop3_b32 v15, v4, v211, 7 bitop3:0x6c
	v_or_b32_e32 v6, s34, v6
	v_and_b32_e32 v17, 24, v8
	v_and_b32_e32 v19, 32, v9
	v_lshlrev_b64 v[8:9], 8, v[0:1]
	s_lshl_b32 s34, s2, 10
	v_lshlrev_b32_e32 v212, 3, v194
	v_and_or_b32 v16, s35, 2, v213
	v_lshl_or_b32 v8, v10, 4, v8
	s_add_i32 s35, s34, 0
	v_lshlrev_b64 v[4:5], 8, v[4:5]
	v_lshlrev_b32_e32 v15, 4, v15
	v_lshrrev_b32_e32 v132, 1, v194
	v_and_b32_e32 v132, 0x80, v132
	v_xor_b32_e32 v8, v8, v132
	v_xor_b32_e32 v15, v15, v132
	v_and_b32_e32 v13, 24, v212
	v_ashrrev_i32_e32 v3, 31, v2
	v_lshl_add_u64 v[10:11], s[36:37], 0, v[8:9]
	s_mov_b32 m0, s35
	v_or_b32_e32 v4, v4, v15
	v_ashrrev_i32_e32 v7, 31, v6
	global_load_lds_dwordx4 v[10:11], off
	v_lshl_add_u64 v[128:129], v[10:11], 0, s[18:19]
	v_lshl_add_u64 v[4:5], s[36:37], 0, v[4:5]
	v_lshl_add_u64 v[130:131], v[4:5], 0, s[18:19]
	s_add_i32 m0, s35, 0x2000
	v_lshlrev_b32_e32 v1, 6, v14
	v_lshlrev_b32_e32 v10, 1, v13
	v_lshlrev_b64 v[2:3], 9, v[2:3]
	global_load_lds_dwordx4 v[4:5], off
	s_add_i32 m0, s35, 0x4000
	s_nop 0
	global_load_lds_dwordx4 v[128:129], off
	s_add_i32 m0, s35, 0x6000
	s_nop 0
	global_load_lds_dwordx4 v[130:131], off
	v_or3_b32 v4, v1, v10, v2
	v_lshrrev_b32_e32 v132, 11, v4
	v_lshrrev_b32_e32 v133, 12, v4
	v_xor_b32_e32 v132, v132, v133
	v_and_b32_e32 v132, 1, v132
	v_mul_u32_u24_e32 v132, 0x1800, v132
	v_xor_b32_e32 v4, v4, v132
	v_mov_b32_e32 v5, v3
	v_lshlrev_b32_e32 v1, 6, v16
	v_lshlrev_b64 v[6:7], 9, v[6:7]
	v_lshl_add_u64 v[4:5], s[30:31], 0, v[4:5]
	s_add_i32 m0, s35, 0x8000
	v_or3_b32 v10, v1, v10, v6
	v_lshrrev_b32_e32 v132, 11, v10
	v_lshrrev_b32_e32 v133, 12, v10
	v_xor_b32_e32 v132, v132, v133
	v_and_b32_e32 v132, 1, v132
	v_mul_u32_u24_e32 v132, 0x1800, v132
	v_xor_b32_e32 v10, v10, v132
	v_mov_b32_e32 v11, v7
	global_load_lds_dwordx4 v[4:5], off
	v_lshl_add_u64 v[10:11], s[30:31], 0, v[10:11]
	s_add_i32 m0, s35, 0xa000
	v_lshl_add_u64 v[4:5], v[4:5], 0, s[10:11]
	global_load_lds_dwordx4 v[10:11], off
	s_add_i32 m0, s35, 0xc000
	v_and_b32_e32 v216, 1, v215
	global_load_lds_dwordx4 v[4:5], off
	v_lshl_add_u64 v[4:5], v[10:11], 0, s[10:11]
	s_add_i32 m0, s35, 0xe000
	v_lshlrev_b32_e32 v20, 13, v216
	global_load_lds_dwordx4 v[4:5], off
	s_cmp_lg_u32 s33, -1
	v_lshl_or_b32 v1, v214, 8, v20
	s_cselect_b32 s30, s33, 0
	s_and_b32 s2, s2, 1
	v_lshlrev_b32_e32 v4, 4, v194
	v_add_u32_e32 v220, 0, v1
	s_lshl_b32 s2, s2, 6
	v_and_b32_e32 v1, 32, v194
	v_and_b32_e32 v5, 0x70, v4
	v_bitop3_b32 v229, v198, v4, s58 bitop3:0x78
	v_or3_b32 v4, s2, v1, v13
	s_and_b32 s2, s3, 1
	s_lshl_b32 s2, s2, 6
	v_or3_b32 v1, s2, v1, v13
	v_add_u32_e32 v0, 32, v0
	v_and_b32_e32 v18, 0xc0, v197
	s_waitcnt vmcnt(0)
	v_lshl_or_b32 v6, v1, 1, v6
	v_ashrrev_i32_e32 v1, 31, v0
	s_waitcnt lgkmcnt(0)
	s_barrier
; __device__ __forceinline__ int v_rd_base(int lane) { return ((lane & 3) << 3) | (((lane >> 2) & 3) << 6) | (((lane >> 4) & 1) << 5) | (((lane >> 5) & 1) << 8); }
; #define RAWBAR() do { asm volatile("s_waitcnt lgkmcnt(0)" ::: "memory"); __builtin_amdgcn_s_barrier(); asm volatile("" ::: "memory"); } while (0)
; #define RAWBAR() do { asm volatile("s_waitcnt lgkmcnt(0)" ::: "memory"); __builtin_amdgcn_s_barrier(); asm volatile("" ::: "memory"); } while (0)
; #define RAWBAR() do { asm volatile("s_waitcnt lgkmcnt(0)" ::: "memory"); __builtin_amdgcn_s_barrier(); asm volatile("" ::: "memory"); } while (0)
; template <int MODE> ...
;     ...
;   f32x16 o[8] = {}; bf16x8 qr[8]; float lsum = 0.f;
;   const bf16* Qw = Qb + (long)(g * 32 + r32) * 128 + hi * 8;
; #pragma unroll
;   for (int d0 = 0; d0 < 8; ++d0) qr[d0] = St::ld8(Qw + d0 * 16);
;   const int vb0 = (int)(uintptr_t)V_lds + v_rd_base(lane) + 2 * kh * 4096;
;   const int krow = 32 * kh + r32;
;   typedef __attribute__((address_space(3))) unsigned lds_u32;
;   const int wu = __builtin_amdgcn_readfirstlane(wid);
;   long gk[2], gv[2];
; #pragma unroll
;   for (int c = 0; c < 2; ++c) { const int q = wu + 8 * c;
;     const int r = 4 * q + (lane >> 4), pch = lane & 15; gk[c] = (long)r * 128 + ((pch ^ (r & 7)) * 8);
;     const int st = 2 * q + (lane >> 5), kk = (st >> 2) * 8 + ((lane >> 2) & 7), k = (kk & ~0xC) | ((kk & 4) << 1) | ((kk & 8) >> 1), cc = (st & 3) * 32 + (lane & 3) * 8;
;     gv[c] = (long)k * 256 + cc; }
;     ...
;   const int NT = seq / KVBLK;
;   STAGE(0, 0); asm volatile("s_waitcnt vmcnt(0)" ::: "memory"); RAWBAR();
;   if (false) __builtin_amdgcn_s_setprio(1);
;   for (int j = 0; j < NT; ++j) {
;     const int buf = j & 1;
;     if (j + 1 < NT) { STAGE((j + 1) * KVBLK, buf ^ 1); }
;     const char* Kb = K_lds + buf * 16384;
;     f32x16 pe = {}, po = {};
; #pragma unroll
;     for (int d0 = 0; d0 < 8; d0 += 2) {
;       const bf16x8 k0 = *reinterpret_cast<const bf16x8*>(Kb + KSWZ(krow, (d0 * 16 + hi * 8) * 2));
;       const bf16x8 k1 = *reinterpret_cast<const bf16x8*>(Kb + KSWZ(krow, ((d0 + 1) * 16 + hi * 8) * 2));
;       pe = __builtin_amdgcn_mfma_f32_32x32x16_bf16(k0, qr[d0], pe, 0, 0, 0);
;       po = __builtin_amdgcn_mfma_f32_32x32x16_bf16(k1, qr[d0 + 1], po, 0, 0, 0); }
	v_add_u32_e32 v10, s30, v18
	v_readlane_b32 s84, v251, 28
	v_lshlrev_b64 v[0:1], 8, v[0:1]
	v_add3_u32 v10, v10, v17, v19
	v_lshl_or_b32 v2, v4, 1, v2
	v_readlane_b32 s85, v251, 29
	v_or_b32_e32 v0, v0, v15
	v_mov_b32_e32 v219, 0
	s_mov_b32 s40, 0
	v_add3_u32 v218, v10, v12, v20
	v_bitop3_b32 v228, v198, v5, 32 bitop3:0x36
	v_bitop3_b32 v227, v198, v5, 64 bitop3:0x36
	v_bitop3_b32 v226, v198, v5, s43 bitop3:0x36
	v_bitop3_b32 v225, v198, v5, s59 bitop3:0x36
	v_bitop3_b32 v223, v198, v5, s60 bitop3:0x36
	v_bitop3_b32 v222, v198, v5, s56 bitop3:0x36
	v_bitop3_b32 v221, v198, v5, s61 bitop3:0x36
	v_lshl_add_u64 v[200:201], s[84:85], 0, v[2:3]
	v_lshl_add_u64 v[202:203], s[84:85], 0, v[6:7]
	v_lshl_add_u64 v[204:205], s[8:9], 0, v[8:9]
	v_lshl_add_u64 v[206:207], s[8:9], 0, v[0:1]
	v_mov_b32_e32 v0, 0
	v_mov_b32_e32 v1, v219
	v_mov_b32_e32 v2, v219
	v_mov_b32_e32 v3, v219
	v_mov_b32_e32 v4, v219
	v_mov_b32_e32 v5, v219
	v_mov_b32_e32 v6, v219
	v_mov_b32_e32 v7, v219
	v_mov_b32_e32 v8, v219
	v_mov_b32_e32 v9, v219
	v_mov_b32_e32 v10, v219
	v_mov_b32_e32 v11, v219
	v_mov_b32_e32 v12, v219
	v_mov_b32_e32 v13, v219
	v_mov_b32_e32 v14, v219
	v_mov_b32_e32 v15, v219
	v_mov_b32_e32 v48, 0
	v_mov_b32_e32 v49, v219
	v_mov_b32_e32 v50, v219
	v_mov_b32_e32 v51, v219
	v_mov_b32_e32 v52, v219
	v_mov_b32_e32 v53, v219
	v_mov_b32_e32 v54, v219
	v_mov_b32_e32 v55, v219
	v_mov_b32_e32 v56, v219
	v_mov_b32_e32 v57, v219
	v_mov_b32_e32 v58, v219
	v_mov_b32_e32 v59, v219
	v_mov_b32_e32 v60, v219
	v_mov_b32_e32 v61, v219
	v_mov_b32_e32 v62, v219
	v_mov_b32_e32 v63, v219
	v_mov_b32_e32 v16, 0
	v_mov_b32_e32 v17, v219
	v_mov_b32_e32 v18, v219
	v_mov_b32_e32 v19, v219
	v_mov_b32_e32 v20, v219
	v_mov_b32_e32 v21, v219
	v_mov_b32_e32 v22, v219
	v_mov_b32_e32 v23, v219
	v_mov_b32_e32 v24, v219
	v_mov_b32_e32 v25, v219
	v_mov_b32_e32 v26, v219
	v_mov_b32_e32 v27, v219
	v_mov_b32_e32 v28, v219
	v_mov_b32_e32 v29, v219
	v_mov_b32_e32 v30, v219
	v_mov_b32_e32 v31, v219
	v_mov_b32_e32 v32, 0
	v_mov_b32_e32 v33, v219
	v_mov_b32_e32 v34, v219
	v_mov_b32_e32 v35, v219
	v_mov_b32_e32 v36, v219
	v_mov_b32_e32 v37, v219
	v_mov_b32_e32 v38, v219
	v_mov_b32_e32 v39, v219
	v_mov_b32_e32 v40, v219
	v_mov_b32_e32 v41, v219
	v_mov_b32_e32 v42, v219
	v_mov_b32_e32 v43, v219
	v_mov_b32_e32 v44, v219
	v_mov_b32_e32 v45, v219
	v_mov_b32_e32 v46, v219
	v_mov_b32_e32 v47, v219
	v_mov_b32_e32 v64, 0
	v_mov_b32_e32 v65, v219
	v_mov_b32_e32 v66, v219
	v_mov_b32_e32 v67, v219
	v_mov_b32_e32 v68, v219
	v_mov_b32_e32 v69, v219
	v_mov_b32_e32 v70, v219
	v_mov_b32_e32 v71, v219
	v_mov_b32_e32 v72, v219
	v_mov_b32_e32 v73, v219
	v_mov_b32_e32 v74, v219
	v_mov_b32_e32 v75, v219
	v_mov_b32_e32 v76, v219
	v_mov_b32_e32 v77, v219
	v_mov_b32_e32 v78, v219
	v_mov_b32_e32 v79, v219
	v_mov_b32_e32 v80, 0
	v_mov_b32_e32 v81, v219
	v_mov_b32_e32 v82, v219
	v_mov_b32_e32 v83, v219
	v_mov_b32_e32 v84, v219
	v_mov_b32_e32 v85, v219
	v_mov_b32_e32 v86, v219
	v_mov_b32_e32 v87, v219
	v_mov_b32_e32 v88, v219
	v_mov_b32_e32 v89, v219
	v_mov_b32_e32 v90, v219
	v_mov_b32_e32 v91, v219
	v_mov_b32_e32 v92, v219
	v_mov_b32_e32 v93, v219
	v_mov_b32_e32 v94, v219
	v_mov_b32_e32 v95, v219
	v_mov_b32_e32 v96, 0
	v_mov_b32_e32 v97, v219
	v_mov_b32_e32 v98, v219
	v_mov_b32_e32 v99, v219
	v_mov_b32_e32 v100, v219
	v_mov_b32_e32 v101, v219
	v_mov_b32_e32 v102, v219
	v_mov_b32_e32 v103, v219
	v_mov_b32_e32 v104, v219
	v_mov_b32_e32 v105, v219
	v_mov_b32_e32 v106, v219
	v_mov_b32_e32 v107, v219
	v_mov_b32_e32 v108, v219
	v_mov_b32_e32 v109, v219
	v_mov_b32_e32 v110, v219
	v_mov_b32_e32 v111, v219
	v_mov_b32_e32 v112, 0
	v_mov_b32_e32 v113, v219
	v_mov_b32_e32 v114, v219
	v_mov_b32_e32 v115, v219
	v_mov_b32_e32 v116, v219
	v_mov_b32_e32 v117, v219
	v_mov_b32_e32 v118, v219
	v_mov_b32_e32 v119, v219
	v_mov_b32_e32 v120, v219
	v_mov_b32_e32 v121, v219
	v_mov_b32_e32 v122, v219
	v_mov_b32_e32 v123, v219
	v_mov_b32_e32 v124, v219
	v_mov_b32_e32 v125, v219
	v_mov_b32_e32 v126, v219
	v_mov_b32_e32 v127, v219
	v_readlane_b32 s86, v251, 30
	v_readlane_b32 s87, v251, 31
	s_waitcnt vmcnt(0)
	v_subrev_u32_e32 v225, s8, v204
	v_subrev_u32_e32 v223, s8, v206
	v_subrev_u32_e32 v222, s84, v200
	v_subrev_u32_e32 v221, s84, v202
	v_lshrrev_b32_e32 v246, 11, v222
	v_lshrrev_b32_e32 v247, 12, v222
	v_xor_b32_e32 v246, v246, v247
	v_and_b32_e32 v246, 1, v246
	v_mul_u32_u24_e32 v246, 0x1800, v246
	v_xor_b32_e32 v222, v222, v246
	v_lshrrev_b32_e32 v246, 11, v221
	v_lshrrev_b32_e32 v247, 12, v221
	v_xor_b32_e32 v246, v246, v247
	v_and_b32_e32 v246, 1, v246
	v_mul_u32_u24_e32 v246, 0x1800, v246
	v_xor_b32_e32 v221, v221, v246
	v_add_u32_e32 v246, 0x100, v222
	v_add_u32_e32 v247, 0x100, v221
	s_add_u32 s86, s8, s26
	s_addc_u32 s87, s9, s27
	s_add_u32 s86, s86, 0x4000
	s_addc_u32 s87, s87, 0
	s_add_u32 s2, s84, s26
	s_addc_u32 s3, s85, s27
	s_add_u32 s2, s2, s12
	s_addc_u32 s3, s3, s13
	v_add_u32_e32 v229, v220, v229
	v_add_u32_e32 v228, v220, v228
	v_add_u32_e32 v227, v220, v227
	v_add_u32_e32 v226, v220, v226
	v_and_b32_e32 v204, 16, v194
	v_lshlrev_b32_e32 v204, 3, v204
	v_add_u32_e32 v226, v226, v204
	v_xor_b32_e32 v207, 0x80, v226
	v_add_u32_e32 v227, v227, v204
	v_xor_b32_e32 v206, 0x80, v227
	v_add_u32_e32 v228, v228, v204
	v_xor_b32_e32 v205, 0x80, v228
	v_add_u32_e32 v229, v229, v204
	v_xor_b32_e32 v204, 0x80, v229
	ds_read_b128 v[230:233], v229
	ds_read_b128 v[234:237], v228
	s_waitcnt lgkmcnt(0)
	v_mfma_f32_32x32x16_bf16 v[144:159], v[230:233], v[188:191], 0
	v_mfma_f32_32x32x16_bf16 v[144:159], v[234:237], v[184:187], v[144:159]
	ds_read_b128 v[230:233], v227
	ds_read_b128 v[234:237], v226
	s_waitcnt lgkmcnt(0)
	v_mfma_f32_32x32x16_bf16 v[144:159], v[230:233], v[180:183], v[144:159]
	v_mfma_f32_32x32x16_bf16 v[144:159], v[234:237], v[176:179], v[144:159]
	ds_read_b128 v[230:233], v204
	ds_read_b128 v[234:237], v205
	s_waitcnt lgkmcnt(0)
	v_mfma_f32_32x32x16_bf16 v[144:159], v[230:233], v[172:175], v[144:159]
	v_mfma_f32_32x32x16_bf16 v[144:159], v[234:237], v[168:171], v[144:159]
	ds_read_b128 v[230:233], v206
	ds_read_b128 v[234:237], v207
	s_waitcnt lgkmcnt(0)
	v_mfma_f32_32x32x16_bf16 v[144:159], v[230:233], v[164:167], v[144:159]
	v_mfma_f32_32x32x16_bf16 v[144:159], v[234:237], v[160:163], v[144:159]
	s_mov_b32 s84, 0
	s_barrier
	s_cmp_lt_u32 s34, 0x1000
	s_cbranch_scc0 .LattnBpre_m1

; #define XS_WRITE(OV, BASE) do { float* xs_ = (float*)(lds + (BASE)) + ((g * 4) * 64 + lane) * 16; \
;     _Pragma("unroll") for (int d0 = 0; d0 < 4; ++d0) { float* xp = xs_ + d0 * 64 * 16; \
;       _Pragma("unroll") for (int q4 = 0; q4 < 4; ++q4) *(f32x4v*)(xp + 4 * q4) = (f32x4v){OV[d0][4 * q4], OV[d0][4 * q4 + 1], OV[d0][4 * q4 + 2], OV[d0][4 * q4 + 3]}; } } while (0)
; #define XS_WRITE(OV, BASE) do { float* xs_ = (float*)(lds + (BASE)) + ((g * 4) * 64 + lane) * 16; \
;     _Pragma("unroll") for (int d0 = 0; d0 < 4; ++d0) { float* xp = xs_ + d0 * 64 * 16; \
;       _Pragma("unroll") for (int q4 = 0; q4 < 4; ++q4) *(f32x4v*)(xp + 4 * q4) = (f32x4v){OV[d0][4 * q4], OV[d0][4 * q4 + 1], OV[d0][4 * q4 + 2], OV[d0][4 * q4 + 3]}; } } while (0)
; template <int MODE> ...
;     ...
;   L_lds[(wid * 2 + hi) * 32 + r32] = lsum;
;     ...
;   f32x16* olo = o; f32x16* ohi = o + 4;
;   if (kh) { XS_WRITE(olo, 0); } else { XS_WRITE(ohi, 65536); }
;   __syncthreads();
;   if (kh) { XS_ADD(ohi, 65536);
; #pragma unroll
;     for (int d0 = 0; d0 < 4; ++d0) o[d0] = o[4 + d0]; }
;   else { XS_ADD(olo, 0); }
.Lattn_join_m1:
	v_mov_b32_e32 v172, v219
	s_setprio 0
	v_lshl_add_u32 v128, v194, 2, 0
	v_add_u32_e32 v128, 0x20000, v128
	v_mov_b32_e32 v129, s65
	v_cmp_eq_u32_e32 vcc, 0, v216
	ds_write_b32 v128, v172
	v_lshlrev_b32_e32 v128, 14, v217
	v_cndmask_b32_e32 v131, 0, v129, vcc
	v_lshlrev_b32_e32 v130, 0, v197
	v_cndmask_b32_e32 v147, v115, v35, vcc
	v_cndmask_b32_e32 v146, v114, v34, vcc
	v_cndmask_b32_e32 v145, v113, v33, vcc
	v_cndmask_b32_e32 v144, v112, v32, vcc
	v_add3_u32 v131, v131, v128, v130
	v_cndmask_b32_e32 v135, v127, v47, vcc
	v_cndmask_b32_e32 v134, v126, v46, vcc
	v_cndmask_b32_e32 v133, v125, v45, vcc
	v_cndmask_b32_e32 v132, v124, v44, vcc
	v_cndmask_b32_e32 v139, v123, v43, vcc
	v_cndmask_b32_e32 v138, v122, v42, vcc
	v_cndmask_b32_e32 v137, v121, v41, vcc
	v_cndmask_b32_e32 v136, v120, v40, vcc
	v_cndmask_b32_e32 v143, v119, v39, vcc
	v_cndmask_b32_e32 v142, v118, v38, vcc
	v_cndmask_b32_e32 v141, v117, v37, vcc
	v_cndmask_b32_e32 v140, v116, v36, vcc
	v_cndmask_b32_e32 v151, v111, v31, vcc
	v_cndmask_b32_e32 v150, v110, v30, vcc
	v_cndmask_b32_e32 v149, v109, v29, vcc
	v_cndmask_b32_e32 v148, v108, v28, vcc
	v_cndmask_b32_e32 v155, v107, v27, vcc
	v_cndmask_b32_e32 v154, v106, v26, vcc
	v_cndmask_b32_e32 v153, v105, v25, vcc
	v_cndmask_b32_e32 v152, v104, v24, vcc
	v_cndmask_b32_e32 v159, v103, v23, vcc
	v_cndmask_b32_e32 v158, v102, v22, vcc
	v_cndmask_b32_e32 v157, v101, v21, vcc
	v_cndmask_b32_e32 v156, v100, v20, vcc
	v_cndmask_b32_e32 v163, v99, v19, vcc
	v_cndmask_b32_e32 v162, v98, v18, vcc
	v_cndmask_b32_e32 v161, v97, v17, vcc
	v_cndmask_b32_e32 v160, v96, v16, vcc
	v_cndmask_b32_e32 v167, v95, v63, vcc
	v_cndmask_b32_e32 v166, v94, v62, vcc
	v_cndmask_b32_e32 v165, v93, v61, vcc
	v_cndmask_b32_e32 v164, v92, v60, vcc
	v_cndmask_b32_e32 v171, v91, v59, vcc
	v_cndmask_b32_e32 v170, v90, v58, vcc
	v_cndmask_b32_e32 v169, v89, v57, vcc
	v_cndmask_b32_e32 v168, v88, v56, vcc
	v_cndmask_b32_e32 v175, v87, v55, vcc
	v_cndmask_b32_e32 v174, v86, v54, vcc
	v_cndmask_b32_e32 v173, v85, v53, vcc
	v_cndmask_b32_e32 v172, v84, v52, vcc
	v_cndmask_b32_e32 v179, v83, v51, vcc
	v_cndmask_b32_e32 v178, v82, v50, vcc
	v_cndmask_b32_e32 v177, v81, v49, vcc
	v_cndmask_b32_e32 v176, v80, v48, vcc
	v_cndmask_b32_e32 v183, v79, v15, vcc
	v_cndmask_b32_e32 v182, v78, v14, vcc
	v_cndmask_b32_e32 v181, v77, v13, vcc
	v_cndmask_b32_e32 v180, v76, v12, vcc
	v_cndmask_b32_e32 v187, v75, v11, vcc
	v_cndmask_b32_e32 v186, v74, v10, vcc
	v_cndmask_b32_e32 v185, v73, v9, vcc
	v_cndmask_b32_e32 v184, v72, v8, vcc
	v_cndmask_b32_e32 v191, v71, v7, vcc
	v_cndmask_b32_e32 v190, v70, v6, vcc
	v_cndmask_b32_e32 v189, v69, v5, vcc
	v_cndmask_b32_e32 v188, v68, v4, vcc
	v_cndmask_b32_e32 v203, v67, v3, vcc
	v_cndmask_b32_e32 v202, v66, v2, vcc
	v_cndmask_b32_e32 v201, v65, v1, vcc
	v_cndmask_b32_e32 v200, v64, v0, vcc
	ds_write_b128 v131, v[144:147]
	ds_write_b128 v131, v[140:143] offset:1024
	ds_write_b128 v131, v[136:139] offset:2048
	ds_write_b128 v131, v[132:135] offset:3072
	ds_write_b128 v131, v[160:163] offset:4096
	ds_write_b128 v131, v[156:159] offset:5120
	ds_write_b128 v131, v[152:155] offset:6144
	ds_write_b128 v131, v[148:151] offset:7168
	ds_write_b128 v131, v[176:179] offset:8192
	ds_write_b128 v131, v[172:175] offset:9216
	ds_write_b128 v131, v[168:171] offset:10240
	ds_write_b128 v131, v[164:167] offset:11264
	ds_write_b128 v131, v[200:203] offset:12288
	ds_write_b128 v131, v[188:191] offset:13312
	ds_write_b128 v131, v[184:187] offset:14336
	ds_write_b128 v131, v[180:183] offset:15360
	s_waitcnt vmcnt(0) lgkmcnt(0)
	s_barrier
	s_and_saveexec_b64 s[26:27], vcc
	s_cbranch_execz .LBB0_1026
	v_mov_b64_e32 v[32:33], v[112:113]
	v_mov_b64_e32 v[16:17], v[96:97]
	v_mov_b64_e32 v[48:49], v[80:81]
	v_mov_b64_e32 v[0:1], v[64:65]
	v_mov_b32_e32 v129, 0
	v_mov_b64_e32 v[34:35], v[114:115]
	v_mov_b64_e32 v[36:37], v[116:117]
	v_mov_b64_e32 v[38:39], v[118:119]
	v_mov_b64_e32 v[40:41], v[120:121]
	v_mov_b64_e32 v[42:43], v[122:123]
	v_mov_b64_e32 v[44:45], v[124:125]
	v_mov_b64_e32 v[46:47], v[126:127]
	v_mov_b64_e32 v[18:19], v[98:99]
	v_mov_b64_e32 v[20:21], v[100:101]
	v_mov_b64_e32 v[22:23], v[102:103]
	v_mov_b64_e32 v[24:25], v[104:105]
	v_mov_b64_e32 v[26:27], v[106:107]
	v_mov_b64_e32 v[28:29], v[108:109]
	v_mov_b64_e32 v[30:31], v[110:111]
	v_mov_b64_e32 v[50:51], v[82:83]
	v_mov_b64_e32 v[52:53], v[84:85]
	v_mov_b64_e32 v[54:55], v[86:87]
	v_mov_b64_e32 v[56:57], v[88:89]
	v_mov_b64_e32 v[58:59], v[90:91]
	v_mov_b64_e32 v[60:61], v[92:93]
	v_mov_b64_e32 v[62:63], v[94:95]
	v_mov_b64_e32 v[2:3], v[66:67]
	v_mov_b64_e32 v[4:5], v[68:69]
	v_mov_b64_e32 v[6:7], v[70:71]
	v_mov_b64_e32 v[8:9], v[72:73]
	v_mov_b64_e32 v[10:11], v[74:75]
	v_mov_b64_e32 v[12:13], v[76:77]
	v_mov_b64_e32 v[14:15], v[78:79]
; __device__ __forceinline__ int crow(int r, int hi) { return (r & 3) + 8 * (r >> 2) + 4 * hi; }
; template <int MODE> ...
;     ...
;   if (kh) { XS_ADD(ohi, 65536);
; #pragma unroll
;     for (int d0 = 0; d0 < 4; ++d0) o[d0] = o[4 + d0]; }
;   else { XS_ADD(olo, 0); }
;     ...
;   float rli[16];
; #pragma unroll
;   for (int r = 0; r < 16; ++r) { const int row = crow(r, hi); const float* lp = L_lds + (g * 4) * 32 + row; rli[r] = __builtin_amdgcn_rcpf((lp[0] + lp[32]) + (lp[64] + lp[96])); }
;   float* Ow = Ob + (long)(g * 32) * LDO + kh * 128;
;   if (MODE == 0) {
; #pragma unroll
;     for (int r = 0; r < 16; ++r) { const int orow = crow(r, hi);
; #pragma unroll
;       for (int d0 = 0; d0 < 4; ++d0) Ow[(long)orow * LDO + d0 * 32 + r32] = o[d0][r] * rli[r]; }
;     asm volatile("s_waitcnt vmcnt(0)" ::: "memory"); __syncthreads();
;   } else {
;     float ssq[16];
; #pragma unroll
;     for (int r = 0; r < 16; ++r) { const int orow = crow(r, hi); float s = 0.f;
; #pragma unroll
;       for (int d0 = 0; d0 < 4; ++d0) { const float v = Ow[(long)orow * LDO + d0 * 32 + r32] - lam * (o[d0][r] * rli[r]); o[d0][r] = v; s += v * v; }
.LBB0_1026:
	s_or_b64 exec, exec, s[26:27]
	v_add3_u32 v110, v129, v128, v130
	ds_read_b128 v[88:91], v110
	ds_read_b128 v[80:83], v110 offset:1024
	ds_read_b128 v[72:75], v110 offset:2048
	ds_read_b128 v[64:67], v110 offset:3072
	ds_read_b128 v[96:99], v110 offset:8192
	ds_read_b128 v[92:95], v110 offset:4096
	ds_read_b128 v[84:87], v110 offset:5120
	ds_read_b128 v[76:79], v110 offset:6144
	ds_read_b128 v[68:71], v110 offset:7168
	ds_read_b128 v[100:103], v110 offset:9216
	ds_read_b128 v[106:109], v110 offset:10240
	s_waitcnt lgkmcnt(6)
	v_pk_add_f32 v[104:105], v[48:49], v[96:97]
	v_pk_add_f32 v[122:123], v[50:51], v[98:99]
	ds_read_b128 v[48:51], v110 offset:11264
	s_waitcnt lgkmcnt(2)
	v_pk_add_f32 v[114:115], v[54:55], v[102:103]
	s_waitcnt lgkmcnt(1)
	v_pk_add_f32 v[102:103], v[56:57], v[106:107]
	v_and_b32_e32 v106, 0x3fffff80, v194
	v_lshlrev_b32_e32 v106, 2, v106
	v_add3_u32 v154, s25, v106, v198
	v_pk_add_f32 v[120:121], v[52:53], v[100:101]
	v_pk_add_f32 v[100:101], v[58:59], v[108:109]
	s_waitcnt lgkmcnt(0)
	v_pk_add_f32 v[98:99], v[60:61], v[48:49]
	v_pk_add_f32 v[96:97], v[62:63], v[50:51]
	ds_read_b128 v[60:63], v110 offset:12288
	ds_read_b128 v[56:59], v110 offset:13312
	ds_read_b128 v[52:55], v110 offset:14336
	ds_read_b128 v[48:51], v110 offset:15360
	ds_read_b128 v[106:109], v154
	ds_read_b128 v[110:113], v154 offset:32
	ds_read_b128 v[116:119], v154 offset:256
	ds_read_b128 v[124:127], v154 offset:128
	ds_read_b128 v[130:133], v154 offset:384
	s_waitcnt lgkmcnt(4)
	v_mov_b32_e32 v128, v106
	ds_read_b128 v[134:137], v154 offset:288
	ds_read_b128 v[138:141], v154 offset:160
	s_waitcnt lgkmcnt(4)
	v_mov_b32_e32 v129, v116
	s_waitcnt lgkmcnt(3)
	v_mov_b32_e32 v146, v124
	s_waitcnt lgkmcnt(2)
	v_mov_b32_e32 v147, v130
	v_pk_add_f32 v[128:129], v[128:129], v[146:147]
	v_mov_b32_e32 v116, v107
	v_add_f32_e32 v106, v128, v129
	v_mov_b32_e32 v130, v125
	v_rcp_f32_e32 v128, v106
	v_pk_add_f32 v[106:107], v[116:117], v[130:131]
	ds_read_b128 v[142:145], v154 offset:416
	v_add_f32_e32 v106, v106, v107
	v_rcp_f32_e32 v129, v106
	v_mov_b32_e32 v106, v108
	v_mov_b32_e32 v107, v118
	v_mov_b32_e32 v116, v126
	v_mov_b32_e32 v117, v132
	v_pk_add_f32 v[106:107], v[106:107], v[116:117]
	v_mov_b32_e32 v118, v109
	v_add_f32_e32 v106, v106, v107
	v_mov_b32_e32 v132, v127
	v_rcp_f32_e32 v126, v106
	v_pk_add_f32 v[106:107], v[118:119], v[132:133]
	s_waitcnt lgkmcnt(1)
	v_mov_b32_e32 v108, v138
	v_add_f32_e32 v106, v106, v107
	v_rcp_f32_e32 v127, v106
	v_mov_b32_e32 v106, v110
	v_mov_b32_e32 v107, v134
	s_waitcnt lgkmcnt(0)
	v_mov_b32_e32 v109, v142
	v_pk_add_f32 v[106:107], v[106:107], v[108:109]
	v_mov_b32_e32 v134, v111
	v_add_f32_e32 v106, v106, v107
	v_mov_b32_e32 v142, v139
	v_rcp_f32_e32 v124, v106
	v_pk_add_f32 v[106:107], v[134:135], v[142:143]
	v_mov_b32_e32 v108, v140
	v_add_f32_e32 v106, v106, v107
	v_rcp_f32_e32 v125, v106
	v_mov_b32_e32 v106, v112
	v_mov_b32_e32 v107, v136
	v_mov_b32_e32 v109, v144
	v_pk_add_f32 v[106:107], v[106:107], v[108:109]
	v_mov_b32_e32 v136, v113
	v_add_f32_e32 v106, v106, v107
	v_mov_b32_e32 v144, v141
	v_rcp_f32_e32 v118, v106
	v_pk_add_f32 v[106:107], v[136:137], v[144:145]
	ds_read_b128 v[108:111], v154 offset:64
	ds_read_b128 v[130:133], v154 offset:192
	ds_read_b128 v[134:137], v154 offset:320
	ds_read_b128 v[138:141], v154 offset:448
	ds_read_b128 v[142:145], v154 offset:96
	v_add_f32_e32 v106, v106, v107
	v_rcp_f32_e32 v119, v106
	s_waitcnt lgkmcnt(4)
	v_mov_b32_e32 v106, v108
	s_waitcnt lgkmcnt(2)
	v_mov_b32_e32 v107, v134
	v_mov_b32_e32 v112, v130
	s_waitcnt lgkmcnt(1)
	v_mov_b32_e32 v113, v138
	v_pk_add_f32 v[106:107], v[106:107], v[112:113]
	v_mov_b32_e32 v134, v109
	v_add_f32_e32 v106, v106, v107
	v_mov_b32_e32 v138, v131
	v_rcp_f32_e32 v108, v106
	v_pk_add_f32 v[106:107], v[134:135], v[138:139]
	v_ashrrev_i32_e32 v197, 31, v196
	v_add_f32_e32 v106, v106, v107
	v_rcp_f32_e32 v109, v106
	v_mov_b32_e32 v106, v110
	v_mov_b32_e32 v107, v136
	v_mov_b32_e32 v136, v111
	v_lshlrev_b64 v[110:111], 13, v[196:197]
	v_lshl_add_u64 v[110:111], s[28:29], 0, v[110:111]
	v_lshlrev_b32_e32 v194, 9, v216
	v_mov_b32_e32 v112, v132
	v_mov_b32_e32 v113, v140
	v_lshl_add_u64 v[110:111], v[110:111], 0, v[194:195]
	v_lshlrev_b32_e32 v194, 2, v214
	v_pk_add_f32 v[106:107], v[106:107], v[112:113]
	v_lshlrev_b32_e32 v112, 15, v213
	v_lshl_add_u64 v[110:111], v[110:111], 0, v[194:195]
	v_mov_b32_e32 v113, v195
	v_lshl_add_u64 v[116:117], v[110:111], 0, v[112:113]
	v_add_co_u32_e32 v110, vcc, s57, v116
	ds_read_b128 v[146:149], v154 offset:352
	ds_read_b128 v[150:153], v154 offset:224
	ds_read_b128 v[154:157], v154 offset:480
	v_addc_co_u32_e32 v111, vcc, 0, v117, vcc
	global_load_dword v134, v[116:117], off
	global_load_dword v135, v[110:111], off
	global_load_dword v138, v[116:117], off offset:128
	global_load_dword v139, v[110:111], off offset:128
	v_mov_b32_e32 v140, v133
	global_load_dword v132, v[116:117], off offset:256
	global_load_dword v133, v[110:111], off offset:256
	v_pk_add_f32 v[112:113], v[136:137], v[140:141]
	global_load_dword v136, v[116:117], off offset:384
	global_load_dword v137, v[110:111], off offset:384
	v_add_f32_e32 v106, v106, v107
	v_add_f32_e32 v107, v112, v113
	s_waitcnt lgkmcnt(3)
	v_mov_b32_e32 v110, v142
	s_waitcnt lgkmcnt(2)
	v_mov_b32_e32 v111, v146
	s_waitcnt lgkmcnt(1)
	v_mov_b32_e32 v112, v150
	s_waitcnt lgkmcnt(0)
; __device__ __forceinline__ int crow(int r, int hi) { return (r & 3) + 8 * (r >> 2) + 4 * hi; }
; template <int MODE> ...
;     ...
;     float ssq[16];
; #pragma unroll
;     for (int r = 0; r < 16; ++r) { const int orow = crow(r, hi); float s = 0.f;
; #pragma unroll
;       for (int d0 = 0; d0 < 4; ++d0) { const float v = Ow[(long)orow * LDO + d0 * 32 + r32] - lam * (o[d0][r] * rli[r]); o[d0][r] = v; s += v * v; }
;       s += __shfl_xor(s, 1); s += __shfl_xor(s, 2); s += __shfl_xor(s, 4); s += __shfl_xor(s, 8); s += __shfl_xor(s, 16);
;       ssq[r] = s; }
	v_mov_b32_e32 v113, v154
	v_pk_add_f32 v[110:111], v[110:111], v[112:113]
	v_mov_b32_e32 v146, v143
	v_add_f32_e32 v110, v110, v111
	v_mov_b32_e32 v154, v151
	v_add_co_u32_e32 v140, vcc, s62, v116
	v_rcp_f32_e32 v112, v110
	v_pk_add_f32 v[110:111], v[146:147], v[154:155]
	v_addc_co_u32_e32 v141, vcc, 0, v117, vcc
	v_add_f32_e32 v110, v110, v111
	v_add_co_u32_e32 v142, vcc, s66, v116
	v_rcp_f32_e32 v113, v110
	v_mov_b32_e32 v110, v144
	v_mov_b32_e32 v111, v148
	v_mov_b32_e32 v148, v145
	v_addc_co_u32_e32 v143, vcc, 0, v117, vcc
	global_load_dword v144, v[140:141], off
	global_load_dword v145, v[142:143], off
	global_load_dword v146, v[140:141], off offset:128
	global_load_dword v147, v[142:143], off offset:128
	v_mov_b32_e32 v130, v152
	v_mov_b32_e32 v131, v156
	v_mov_b32_e32 v156, v153
	v_pk_add_f32 v[110:111], v[110:111], v[130:131]
	v_pk_add_f32 v[130:131], v[148:149], v[156:157]
	global_load_dword v148, v[140:141], off offset:256
	global_load_dword v149, v[142:143], off offset:256
	v_add_f32_e32 v110, v110, v111
	v_add_f32_e32 v111, v130, v131
	v_and_b32_e32 v131, 64, v210
	global_load_dword v140, v[140:141], off offset:384
	s_nop 0
	global_load_dword v141, v[142:143], off offset:384
	v_xor_b32_e32 v130, 1, v210
	v_add_u32_e32 v158, 64, v131
	v_cmp_lt_i32_e32 vcc, v130, v158
	v_pk_add_f32 v[32:33], v[32:33], v[88:89]
	v_pk_add_f32 v[0:1], v[0:1], v[60:61]
	v_cndmask_b32_e32 v130, v210, v130, vcc
	v_lshlrev_b32_e32 v131, 2, v130
	v_xor_b32_e32 v130, 2, v210
	v_cmp_lt_i32_e32 vcc, v130, v158
	v_pk_mul_f32 v[32:33], v[32:33], v[128:129]
	v_pk_add_f32 v[16:17], v[16:17], v[92:93]
	v_cndmask_b32_e32 v130, v210, v130, vcc
	v_add_co_u32_e32 v142, vcc, s64, v116
	v_xor_b32_e32 v159, 4, v210
	s_nop 0
	v_addc_co_u32_e32 v143, vcc, 0, v117, vcc
	v_add_co_u32_e32 v150, vcc, s67, v116
	v_pk_mul_f32 v[16:17], v[16:17], v[128:129]
	s_nop 0
	v_addc_co_u32_e32 v151, vcc, 0, v117, vcc
	global_load_dword v152, v[142:143], off
	global_load_dword v153, v[150:151], off
	global_load_dword v154, v[142:143], off offset:128
	global_load_dword v155, v[150:151], off offset:128
	global_load_dword v156, v[142:143], off offset:256
	global_load_dword v157, v[150:151], off offset:256
	v_cmp_lt_i32_e32 vcc, v159, v158
	v_pk_mul_f32 v[0:1], v[0:1], v[128:129]
	v_pk_add_f32 v[18:19], v[18:19], v[94:95]
	v_lshlrev_b32_e32 v130, 2, v130
	v_pk_mul_f32 v[18:19], v[18:19], v[126:127]
	v_pk_add_f32 v[2:3], v[2:3], v[62:63]
	v_pk_mul_f32 v[62:63], v[122:123], v[126:127]
	v_pk_mul_f32 v[2:3], v[2:3], v[126:127]
	v_pk_add_f32 v[56:57], v[4:5], v[56:57]
	v_pk_add_f32 v[6:7], v[6:7], v[58:59]
	v_pk_add_f32 v[52:53], v[8:9], v[52:53]
	v_pk_mul_f32 v[6:7], v[6:7], v[118:119]
	s_waitcnt vmcnt(20)
	v_pk_fma_f32 v[60:61], v[192:193], v[32:33], v[134:135] neg_lo:[1,0,0] neg_hi:[1,0,0]
	v_pk_mul_f32 v[32:33], v[104:105], v[128:129]
	s_waitcnt vmcnt(18)
	v_pk_fma_f32 v[88:89], v[192:193], v[16:17], v[138:139] neg_lo:[1,0,0] neg_hi:[1,0,0]
	v_pk_add_f32 v[8:9], v[24:25], v[76:77]
	s_waitcnt vmcnt(16)
	v_pk_fma_f32 v[92:93], v[192:193], v[32:33], v[132:133] neg_lo:[1,0,0] neg_hi:[1,0,0]
	global_load_dword v132, v[142:143], off offset:384
	global_load_dword v133, v[150:151], off offset:384
	v_cndmask_b32_e32 v32, v210, v159, vcc
	v_lshlrev_b32_e32 v129, 2, v32
	v_xor_b32_e32 v32, 8, v210
	v_cmp_lt_i32_e32 vcc, v32, v158
	s_waitcnt vmcnt(16)
	v_pk_fma_f32 v[104:105], v[192:193], v[0:1], v[136:137] neg_lo:[1,0,0] neg_hi:[1,0,0]
	v_pk_mul_f32 v[16:17], v[88:89], v[88:89]
	v_cndmask_b32_e32 v32, v210, v32, vcc
	v_lshlrev_b32_e32 v128, 2, v32
	v_pk_add_f32 v[32:33], v[34:35], v[90:91]
	v_add_co_u32_e32 v90, vcc, s68, v116
	v_pk_fma_f32 v[16:17], v[60:61], v[60:61], v[16:17]
	s_nop 0
	v_addc_co_u32_e32 v91, vcc, 0, v117, vcc
	v_add_co_u32_e32 v94, vcc, s69, v116
	v_pk_fma_f32 v[16:17], v[92:93], v[92:93], v[16:17]
	s_nop 0
	v_addc_co_u32_e32 v95, vcc, 0, v117, vcc
	global_load_dword v134, v[90:91], off
	global_load_dword v135, v[94:95], off
	global_load_dword v136, v[90:91], off offset:128
	global_load_dword v137, v[94:95], off offset:128
	v_pk_fma_f32 v[0:1], v[104:105], v[104:105], v[16:17]
	ds_bpermute_b32 v16, v131, v0
	ds_bpermute_b32 v17, v131, v1
	global_load_dword v138, v[90:91], off offset:256
	global_load_dword v139, v[94:95], off offset:256
	global_load_dword v142, v[90:91], off offset:384
	global_load_dword v143, v[94:95], off offset:384
	v_pk_mul_f32 v[32:33], v[32:33], v[126:127]
	s_waitcnt vmcnt(20)
	v_pk_fma_f32 v[34:35], v[192:193], v[18:19], v[146:147] neg_lo:[1,0,0] neg_hi:[1,0,0]
	s_waitcnt lgkmcnt(0)
	v_pk_add_f32 v[0:1], v[0:1], v[16:17]
	ds_bpermute_b32 v16, v130, v0
	ds_bpermute_b32 v17, v130, v1
	v_pk_fma_f32 v[32:33], v[192:193], v[32:33], v[144:145] neg_lo:[1,0,0] neg_hi:[1,0,0]
	v_pk_mul_f32 v[18:19], v[34:35], v[34:35]
	s_waitcnt vmcnt(18)
	v_pk_fma_f32 v[62:63], v[192:193], v[62:63], v[148:149] neg_lo:[1,0,0] neg_hi:[1,0,0]
	v_pk_fma_f32 v[18:19], v[32:33], v[32:33], v[18:19]
	s_waitcnt lgkmcnt(0)
	v_pk_add_f32 v[0:1], v[0:1], v[16:17]
	v_pk_fma_f32 v[18:19], v[62:63], v[62:63], v[18:19]
	s_waitcnt vmcnt(16)
	v_pk_fma_f32 v[90:91], v[192:193], v[2:3], v[140:141] neg_lo:[1,0,0] neg_hi:[1,0,0]
	ds_bpermute_b32 v16, v129, v0
	v_pk_fma_f32 v[2:3], v[90:91], v[90:91], v[18:19]
	ds_bpermute_b32 v17, v129, v1
	ds_bpermute_b32 v18, v131, v2
	ds_bpermute_b32 v19, v131, v3
	v_xor_b32_e32 v150, 16, v210
	v_cmp_lt_i32_e32 vcc, v150, v158
	s_waitcnt lgkmcnt(2)
	v_pk_add_f32 v[16:17], v[0:1], v[16:17]
	v_pk_add_f32 v[0:1], v[20:21], v[84:85]
	s_waitcnt lgkmcnt(0)
; __device__ __forceinline__ int crow(int r, int hi) { return (r & 3) + 8 * (r >> 2) + 4 * hi; }
; template <int MODE> ...
;     ...
;   float rli[16];
; #pragma unroll
;   for (int r = 0; r < 16; ++r) { const int row = crow(r, hi); const float* lp = L_lds + (g * 4) * 32 + row; rli[r] = __builtin_amdgcn_rcpf((lp[0] + lp[32]) + (lp[64] + lp[96])); }
;   float* Ow = Ob + (long)(g * 32) * LDO + kh * 128;
;   if (MODE == 0) {
; #pragma unroll
;     for (int r = 0; r < 16; ++r) { const int orow = crow(r, hi);
; #pragma unroll
;       for (int d0 = 0; d0 < 4; ++d0) Ow[(long)orow * LDO + d0 * 32 + r32] = o[d0][r] * rli[r]; }
;     asm volatile("s_waitcnt vmcnt(0)" ::: "memory"); __syncthreads();
;   } else {
;     float ssq[16];
; #pragma unroll
;     for (int r = 0; r < 16; ++r) { const int orow = crow(r, hi); float s = 0.f;
; #pragma unroll
;       for (int d0 = 0; d0 < 4; ++d0) { const float v = Ow[(long)orow * LDO + d0 * 32 + r32] - lam * (o[d0][r] * rli[r]); o[d0][r] = v; s += v * v; }
;       s += __shfl_xor(s, 1); s += __shfl_xor(s, 2); s += __shfl_xor(s, 4); s += __shfl_xor(s, 8); s += __shfl_xor(s, 16);
;       ssq[r] = s; }
;     __syncthreads();
	v_pk_add_f32 v[18:19], v[2:3], v[18:19]
	v_pk_add_f32 v[2:3], v[36:37], v[80:81]
	v_pk_mul_f32 v[0:1], v[0:1], v[124:125]
	v_pk_mul_f32 v[2:3], v[2:3], v[124:125]
	v_cndmask_b32_e32 v94, v210, v150, vcc
	v_pk_mul_f32 v[36:37], v[56:57], v[124:125]
	v_lshlrev_b32_e32 v122, 2, v94
	ds_bpermute_b32 v94, v130, v18
	ds_bpermute_b32 v95, v130, v19
	ds_bpermute_b32 v80, v128, v16
	ds_bpermute_b32 v81, v128, v17
	s_waitcnt vmcnt(14)
	v_pk_fma_f32 v[4:5], v[192:193], v[2:3], v[152:153] neg_lo:[1,0,0] neg_hi:[1,0,0]
	v_pk_mul_f32 v[8:9], v[8:9], v[108:109]
	s_waitcnt vmcnt(12)
	v_pk_fma_f32 v[2:3], v[192:193], v[0:1], v[154:155] neg_lo:[1,0,0] neg_hi:[1,0,0]
	s_waitcnt lgkmcnt(2)
	v_pk_add_f32 v[18:19], v[18:19], v[94:95]
	v_pk_mul_f32 v[0:1], v[2:3], v[2:3]
	ds_bpermute_b32 v84, v129, v18
	v_pk_fma_f32 v[20:21], v[4:5], v[4:5], v[0:1]
	v_pk_mul_f32 v[0:1], v[120:121], v[124:125]
	v_add_co_u32_e32 v120, vcc, s63, v116
	s_waitcnt vmcnt(10)
	v_pk_fma_f32 v[0:1], v[192:193], v[0:1], v[156:157] neg_lo:[1,0,0] neg_hi:[1,0,0]
	v_addc_co_u32_e32 v121, vcc, 0, v117, vcc
	v_add_co_u32_e32 v126, vcc, s70, v116
	v_pk_fma_f32 v[20:21], v[0:1], v[0:1], v[20:21]
	s_nop 0
	v_addc_co_u32_e32 v127, vcc, 0, v117, vcc
	global_load_dword v140, v[120:121], off
	global_load_dword v141, v[126:127], off
	global_load_dword v144, v[120:121], off offset:128
	global_load_dword v145, v[126:127], off offset:128
	ds_bpermute_b32 v85, v129, v19
	s_waitcnt lgkmcnt(2)
	v_pk_add_f32 v[80:81], v[16:17], v[80:81]
	s_waitcnt vmcnt(12)
	v_pk_fma_f32 v[36:37], v[192:193], v[36:37], v[132:133] neg_lo:[1,0,0] neg_hi:[1,0,0]
	v_pk_add_f32 v[16:17], v[22:23], v[86:87]
	v_pk_fma_f32 v[20:21], v[36:37], v[36:37], v[20:21]
	ds_bpermute_b32 v56, v131, v20
	ds_bpermute_b32 v57, v131, v21
	s_waitcnt lgkmcnt(2)
	v_pk_add_f32 v[18:19], v[18:19], v[84:85]
	ds_bpermute_b32 v94, v128, v18
	ds_bpermute_b32 v95, v128, v19
	v_pk_mul_f32 v[16:17], v[16:17], v[118:119]
	s_waitcnt lgkmcnt(2)
	v_pk_add_f32 v[20:21], v[20:21], v[56:57]
	ds_bpermute_b32 v56, v130, v20
	ds_bpermute_b32 v57, v130, v21
	s_waitcnt lgkmcnt(2)
	v_pk_add_f32 v[94:95], v[18:19], v[94:95]
	v_pk_add_f32 v[18:19], v[38:39], v[82:83]
	v_add_co_u32_e32 v58, vcc, s71, v116
	s_waitcnt lgkmcnt(0)
	v_pk_add_f32 v[20:21], v[20:21], v[56:57]
	ds_bpermute_b32 v56, v129, v20
	ds_bpermute_b32 v57, v129, v21
	v_pk_mul_f32 v[18:19], v[18:19], v[118:119]
	v_addc_co_u32_e32 v59, vcc, 0, v117, vcc
	s_waitcnt vmcnt(8)
	v_pk_fma_f32 v[16:17], v[192:193], v[16:17], v[136:137] neg_lo:[1,0,0] neg_hi:[1,0,0]
	s_waitcnt lgkmcnt(0)
	v_pk_add_f32 v[124:125], v[20:21], v[56:57]
	global_load_dword v56, v[120:121], off offset:256
	global_load_dword v57, v[126:127], off offset:256
	global_load_dword v38, v[120:121], off offset:384
	global_load_dword v39, v[126:127], off offset:384
	v_pk_fma_f32 v[18:19], v[192:193], v[18:19], v[134:135] neg_lo:[1,0,0] neg_hi:[1,0,0]
	v_pk_mul_f32 v[20:21], v[16:17], v[16:17]
	v_add_co_u32_e32 v82, vcc, s72, v116
	v_pk_fma_f32 v[22:23], v[18:19], v[18:19], v[20:21]
	v_pk_mul_f32 v[20:21], v[114:115], v[118:119]
	v_addc_co_u32_e32 v83, vcc, 0, v117, vcc
	global_load_dword v118, v[58:59], off
	global_load_dword v119, v[82:83], off
	global_load_dword v120, v[58:59], off offset:128
	global_load_dword v121, v[82:83], off offset:128
	global_load_dword v126, v[58:59], off offset:256
	global_load_dword v127, v[82:83], off offset:256
	global_load_dword v134, v[58:59], off offset:384
	global_load_dword v135, v[82:83], off offset:384
	s_waitcnt vmcnt(18)
	v_pk_fma_f32 v[20:21], v[192:193], v[20:21], v[138:139] neg_lo:[1,0,0] neg_hi:[1,0,0]
	s_waitcnt vmcnt(16)
	v_pk_fma_f32 v[6:7], v[192:193], v[6:7], v[142:143] neg_lo:[1,0,0] neg_hi:[1,0,0]
	v_pk_fma_f32 v[22:23], v[20:21], v[20:21], v[22:23]
	ds_bpermute_b32 v132, v128, v124
	v_pk_fma_f32 v[22:23], v[6:7], v[6:7], v[22:23]
	ds_bpermute_b32 v86, v131, v22
	ds_bpermute_b32 v87, v131, v23
	ds_bpermute_b32 v133, v128, v125
	v_rcp_f32_e32 v106, v106
	v_rcp_f32_e32 v107, v107
	v_pk_add_f32 v[26:27], v[26:27], v[78:79]
	s_waitcnt lgkmcnt(1)
	v_pk_add_f32 v[22:23], v[22:23], v[86:87]
	ds_bpermute_b32 v58, v130, v22
	ds_bpermute_b32 v59, v130, v23
	s_waitcnt lgkmcnt(2)
	v_pk_add_f32 v[82:83], v[124:125], v[132:133]
	v_pk_add_f32 v[42:43], v[42:43], v[74:75]
	v_pk_mul_f32 v[26:27], v[26:27], v[106:107]
	v_pk_add_f32 v[10:11], v[10:11], v[54:55]
	s_waitcnt lgkmcnt(0)
	v_pk_add_f32 v[124:125], v[22:23], v[58:59]
	v_pk_add_f32 v[22:23], v[40:41], v[72:73]
	v_add_co_u32_e32 v40, vcc, s73, v116
	v_pk_mul_f32 v[22:23], v[22:23], v[108:109]
	s_nop 0
	v_addc_co_u32_e32 v41, vcc, 0, v117, vcc
	v_add_co_u32_e32 v58, vcc, s74, v116
	v_pk_mul_f32 v[42:43], v[42:43], v[106:107]
	s_nop 0
	v_addc_co_u32_e32 v59, vcc, 0, v117, vcc
	global_load_dword v136, v[40:41], off
	global_load_dword v137, v[58:59], off
	global_load_dword v138, v[40:41], off offset:128
	global_load_dword v139, v[58:59], off offset:128
	v_pk_mul_f32 v[10:11], v[10:11], v[106:107]
	ds_bpermute_b32 v132, v129, v124
	ds_bpermute_b32 v133, v129, v125
	v_rcp_f32_e32 v110, v110
	v_rcp_f32_e32 v111, v111
	ds_bpermute_b32 v84, v122, v80
	ds_bpermute_b32 v85, v122, v81
	s_waitcnt vmcnt(18)
	v_pk_fma_f32 v[22:23], v[192:193], v[22:23], v[140:141] neg_lo:[1,0,0] neg_hi:[1,0,0]
	global_load_dword v140, v[40:41], off offset:256
	global_load_dword v142, v[40:41], off offset:384
	global_load_dword v141, v[58:59], off offset:256
	global_load_dword v143, v[58:59], off offset:384
	v_add_co_u32_e32 v40, vcc, s75, v116
	s_waitcnt vmcnt(20)
	v_pk_fma_f32 v[8:9], v[192:193], v[8:9], v[144:145] neg_lo:[1,0,0] neg_hi:[1,0,0]
	v_addc_co_u32_e32 v41, vcc, 0, v117, vcc
	v_add_co_u32_e32 v72, vcc, s76, v116
	v_pk_mul_f32 v[58:59], v[102:103], v[108:109]
	s_nop 0
	v_addc_co_u32_e32 v73, vcc, 0, v117, vcc
	global_load_dword v116, v[40:41], off
	global_load_dword v117, v[72:73], off
	global_load_dword v144, v[40:41], off offset:128
	global_load_dword v145, v[72:73], off offset:128
	global_load_dword v102, v[40:41], off offset:256
	global_load_dword v103, v[72:73], off offset:256
	global_load_dword v146, v[40:41], off offset:384
	global_load_dword v147, v[72:73], off offset:384
	v_pk_mul_f32 v[24:25], v[8:9], v[8:9]
	v_pk_mul_f32 v[40:41], v[52:53], v[108:109]
	v_pk_fma_f32 v[24:25], v[22:23], v[22:23], v[24:25]
	ds_bpermute_b32 v114, v122, v94
	ds_bpermute_b32 v115, v122, v95
	ds_bpermute_b32 v86, v122, v82
	ds_bpermute_b32 v87, v122, v83
	v_cmp_eq_u32_e32 vcc, 0, v214
	s_waitcnt lgkmcnt(0)
	s_barrier
; __device__ __forceinline__ int crow(int r, int hi) { return (r & 3) + 8 * (r >> 2) + 4 * hi; }
; template <int MODE> ...
;     ...
;     for (int r = 0; r < 16; ++r) { const int orow = crow(r, hi); float s = 0.f;
; #pragma unroll
;       for (int d0 = 0; d0 < 4; ++d0) { const float v = Ow[(long)orow * LDO + d0 * 32 + r32] - lam * (o[d0][r] * rli[r]); o[d0][r] = v; s += v * v; }
;       s += __shfl_xor(s, 1); s += __shfl_xor(s, 2); s += __shfl_xor(s, 4); s += __shfl_xor(s, 8); s += __shfl_xor(s, 16);
;       ssq[r] = s; }
;     __syncthreads();
;     if (r32 == 0) {
; #pragma unroll
;       for (int r = 0; r < 16; ++r) L_lds[wid * 32 + crow(r, hi)] = ssq[r]; }
	s_waitcnt vmcnt(26)
	v_pk_fma_f32 v[58:59], v[192:193], v[58:59], v[56:57] neg_lo:[1,0,0] neg_hi:[1,0,0]
	s_nop 0
	v_pk_fma_f32 v[24:25], v[58:59], v[58:59], v[24:25]
	s_waitcnt vmcnt(24)
	v_pk_fma_f32 v[72:73], v[192:193], v[40:41], v[38:39] neg_lo:[1,0,0] neg_hi:[1,0,0]
	v_pk_add_f32 v[40:41], v[124:125], v[132:133]
	v_pk_fma_f32 v[24:25], v[72:73], v[72:73], v[24:25]
	ds_bpermute_b32 v38, v131, v24
	ds_bpermute_b32 v39, v131, v25
	ds_bpermute_b32 v76, v128, v40
	s_waitcnt vmcnt(22)
	v_pk_fma_f32 v[56:57], v[192:193], v[42:43], v[118:119] neg_lo:[1,0,0] neg_hi:[1,0,0]
	v_pk_mul_f32 v[42:43], v[100:101], v[106:107]
	s_waitcnt vmcnt(20)
	v_pk_fma_f32 v[54:55], v[192:193], v[26:27], v[120:121] neg_lo:[1,0,0] neg_hi:[1,0,0]
	s_waitcnt vmcnt(18)
	v_pk_fma_f32 v[52:53], v[192:193], v[42:43], v[126:127] neg_lo:[1,0,0] neg_hi:[1,0,0]
	v_pk_mul_f32 v[26:27], v[54:55], v[54:55]
	s_waitcnt vmcnt(16)
	v_pk_fma_f32 v[42:43], v[192:193], v[10:11], v[134:135] neg_lo:[1,0,0] neg_hi:[1,0,0]
	v_pk_fma_f32 v[26:27], v[56:57], v[56:57], v[26:27]
	s_waitcnt lgkmcnt(1)
	v_pk_add_f32 v[24:25], v[24:25], v[38:39]
	v_pk_fma_f32 v[26:27], v[52:53], v[52:53], v[26:27]
	ds_bpermute_b32 v38, v130, v24
	v_pk_fma_f32 v[10:11], v[42:43], v[42:43], v[26:27]
	ds_bpermute_b32 v26, v131, v10
	ds_bpermute_b32 v27, v131, v11
	ds_bpermute_b32 v39, v130, v25
	ds_bpermute_b32 v77, v128, v41
	s_waitcnt lgkmcnt(2)
	v_pk_add_f32 v[10:11], v[10:11], v[26:27]
	s_waitcnt lgkmcnt(1)
	v_pk_add_f32 v[24:25], v[24:25], v[38:39]
	ds_bpermute_b32 v26, v130, v10
	ds_bpermute_b32 v27, v130, v11
	ds_bpermute_b32 v38, v129, v24
	ds_bpermute_b32 v39, v129, v25
	s_waitcnt lgkmcnt(4)
	v_pk_add_f32 v[74:75], v[40:41], v[76:77]
	ds_bpermute_b32 v76, v122, v74
	s_waitcnt lgkmcnt(3)
	v_pk_add_f32 v[10:11], v[10:11], v[26:27]
	ds_bpermute_b32 v26, v129, v10
	s_waitcnt lgkmcnt(2)
	v_pk_add_f32 v[24:25], v[24:25], v[38:39]
	ds_bpermute_b32 v27, v129, v11
	ds_bpermute_b32 v38, v128, v24
	ds_bpermute_b32 v39, v128, v25
	ds_bpermute_b32 v77, v122, v75
	s_waitcnt lgkmcnt(3)
	v_pk_add_f32 v[106:107], v[10:11], v[26:27]
	v_pk_add_f32 v[10:11], v[12:13], v[48:49]
	v_pk_add_f32 v[12:13], v[28:29], v[68:69]
	s_waitcnt lgkmcnt(1)
	v_pk_add_f32 v[78:79], v[24:25], v[38:39]
	v_pk_add_f32 v[24:25], v[44:45], v[64:65]
	v_pk_mul_f32 v[12:13], v[12:13], v[112:113]
	v_pk_mul_f32 v[24:25], v[24:25], v[112:113]
	s_waitcnt vmcnt(12)
	v_pk_fma_f32 v[38:39], v[192:193], v[12:13], v[138:139] neg_lo:[1,0,0] neg_hi:[1,0,0]
	v_pk_fma_f32 v[40:41], v[192:193], v[24:25], v[136:137] neg_lo:[1,0,0] neg_hi:[1,0,0]
	v_pk_mul_f32 v[12:13], v[38:39], v[38:39]
	v_pk_mul_f32 v[24:25], v[98:99], v[112:113]
	v_pk_fma_f32 v[12:13], v[40:41], v[40:41], v[12:13]
	s_waitcnt vmcnt(9)
	v_pk_fma_f32 v[28:29], v[192:193], v[24:25], v[140:141] neg_lo:[1,0,0] neg_hi:[1,0,0]
	v_pk_mul_f32 v[10:11], v[10:11], v[112:113]
	v_pk_fma_f32 v[12:13], v[28:29], v[28:29], v[12:13]
	s_waitcnt vmcnt(8)
	v_pk_fma_f32 v[26:27], v[192:193], v[10:11], v[142:143] neg_lo:[1,0,0] neg_hi:[1,0,0]
	v_pk_add_f32 v[10:11], v[30:31], v[70:71]
	v_pk_fma_f32 v[44:45], v[26:27], v[26:27], v[12:13]
	v_pk_add_f32 v[12:13], v[46:47], v[66:67]
	v_pk_mul_f32 v[10:11], v[10:11], v[110:111]
	v_pk_mul_f32 v[12:13], v[12:13], v[110:111]
	v_pk_add_f32 v[24:25], v[14:15], v[50:51]
	s_waitcnt vmcnt(4)
	v_pk_fma_f32 v[10:11], v[192:193], v[10:11], v[144:145] neg_lo:[1,0,0] neg_hi:[1,0,0]
	v_pk_fma_f32 v[12:13], v[192:193], v[12:13], v[116:117] neg_lo:[1,0,0] neg_hi:[1,0,0]
	v_pk_mul_f32 v[14:15], v[10:11], v[10:11]
	v_pk_mul_f32 v[24:25], v[24:25], v[110:111]
	v_pk_fma_f32 v[30:31], v[12:13], v[12:13], v[14:15]
	v_pk_mul_f32 v[14:15], v[96:97], v[110:111]
	s_waitcnt vmcnt(0)
	v_pk_fma_f32 v[24:25], v[192:193], v[24:25], v[146:147] neg_lo:[1,0,0] neg_hi:[1,0,0]
	v_pk_fma_f32 v[14:15], v[192:193], v[14:15], v[102:103] neg_lo:[1,0,0] neg_hi:[1,0,0]
	ds_bpermute_b32 v48, v131, v44
	v_pk_fma_f32 v[30:31], v[14:15], v[14:15], v[30:31]
	ds_bpermute_b32 v49, v131, v45
	v_pk_fma_f32 v[30:31], v[24:25], v[24:25], v[30:31]
	ds_bpermute_b32 v46, v131, v30
	ds_bpermute_b32 v47, v131, v31
	ds_bpermute_b32 v108, v128, v106
	s_waitcnt lgkmcnt(3)
	v_pk_add_f32 v[44:45], v[44:45], v[48:49]
	ds_bpermute_b32 v48, v130, v44
	ds_bpermute_b32 v49, v130, v45
	s_waitcnt lgkmcnt(3)
	v_pk_add_f32 v[46:47], v[30:31], v[46:47]
	ds_bpermute_b32 v50, v130, v46
	ds_bpermute_b32 v51, v130, v47
	ds_bpermute_b32 v109, v128, v107
	s_waitcnt lgkmcnt(3)
	v_pk_add_f32 v[48:49], v[44:45], v[48:49]
	ds_bpermute_b32 v64, v129, v48
	ds_bpermute_b32 v65, v129, v49
	s_waitcnt lgkmcnt(3)
	v_pk_add_f32 v[46:47], v[46:47], v[50:51]
	ds_bpermute_b32 v50, v129, v46
	ds_bpermute_b32 v51, v129, v47
	s_waitcnt lgkmcnt(4)
	v_pk_add_f32 v[30:31], v[106:107], v[108:109]
	s_waitcnt lgkmcnt(2)
	v_pk_add_f32 v[48:49], v[48:49], v[64:65]
	ds_bpermute_b32 v64, v128, v48
	ds_bpermute_b32 v65, v128, v49
	s_waitcnt lgkmcnt(2)
	v_pk_add_f32 v[50:51], v[46:47], v[50:51]
	ds_bpermute_b32 v66, v128, v50
	ds_bpermute_b32 v67, v128, v51
	ds_bpermute_b32 v100, v122, v78
	s_waitcnt lgkmcnt(3)
	v_pk_add_f32 v[46:47], v[48:49], v[64:65]
	ds_bpermute_b32 v101, v122, v79
	ds_bpermute_b32 v44, v122, v30
	s_waitcnt lgkmcnt(3)
	v_pk_add_f32 v[50:51], v[50:51], v[66:67]
	ds_bpermute_b32 v45, v122, v31
	ds_bpermute_b32 v48, v122, v46
	ds_bpermute_b32 v49, v122, v47
	ds_bpermute_b32 v64, v122, v50
	ds_bpermute_b32 v65, v122, v51
	v_lshlrev_b32_e32 v66, 7, v215
	v_add3_u32 v66, s25, v66, v198
	s_and_saveexec_b64 s[26:27], vcc
	s_cbranch_execz .LBB0_1009
	v_pk_add_f32 v[68:69], v[80:81], v[84:85]
	v_pk_add_f32 v[70:71], v[94:95], v[114:115]
	ds_write_b128 v66, v[68:71]
	v_pk_add_f32 v[68:69], v[82:83], v[86:87]
	v_pk_add_f32 v[70:71], v[74:75], v[76:77]
	ds_write_b128 v66, v[68:71] offset:32
	s_waitcnt lgkmcnt(8)
	v_pk_add_f32 v[68:69], v[78:79], v[100:101]
	s_waitcnt lgkmcnt(6)
	v_pk_add_f32 v[70:71], v[30:31], v[44:45]
	s_waitcnt lgkmcnt(4)
	v_pk_add_f32 v[44:45], v[46:47], v[48:49]
	s_waitcnt lgkmcnt(2)
	v_pk_add_f32 v[46:47], v[50:51], v[64:65]
	ds_write_b128 v66, v[68:71] offset:64
	ds_write_b128 v66, v[44:47] offset:96
	s_branch .LBB0_1009
